# write-through (sc1) epilogue stores for the single-unit GEMM phases (merge, w_out, down) so the grid barrier's L2 write-back has nothing to flush; on top of opt2
# baseline (speedup 1.0000x reference)
; __device__ __forceinline__ unsigned pkh(float lo, float hi) { f32v2_t v; v.x = lo; v.y = hi; return __builtin_bit_cast(unsigned, __builtin_convertvector(v, bf16v2_t)); }
; __device__ __forceinline__ float bf_lo(unsigned w) { return __uint_as_float(w << 16); }
; __device__ __forceinline__ float bf_hi(unsigned w) { return __uint_as_float(w & 0xffff0000u); }
; __device__ __forceinline__ float sigmoidf_(float x) { return 1.0f / (1.0f + __expf(-x)); }
;     template <int MODE> __device__ __forceinline__ void run(const pg8::f32x4 (&acc)[2][2][4][2], const pg8::Unit& u, int wr, int wc, int fr, int fq) const {
;     ...
;                 for (int q = 0; q < 4; ++q) { const int m = 2 * mp + (q >> 1), bj = q & 1; const int row = u.pm * 256 + ai * 128 + wr * 64 + m * 16 + fr, col = u.pn * 256 + bj * 128 + wc * 32 + 8 * fq;
;                     const pg8::f32x4 t0 = acc[ai][bj][m][0], t1 = acc[ai][bj][m][1];
;                     float v[8] = {t0[0], t0[1], t0[2], t0[3], t1[0], t1[1], t1[2], t1[3]};
;                     if constexpr (MODE == 5) {
; #pragma unroll
;                         for (int e = 0; e < 8; ++e) { const float r = fmaxf(v[e], 0.f); v[e] = r * r; }
;                     }
;                     if constexpr (MODE == 6) { const u32x4 g = gpre[q];
;                         v[0] *= sigmoidf_(bf_lo(g.x)); v[1] *= sigmoidf_(bf_hi(g.x)); v[2] *= sigmoidf_(bf_lo(g.y)); v[3] *= sigmoidf_(bf_hi(g.y));
;                         v[4] *= sigmoidf_(bf_lo(g.z)); v[5] *= sigmoidf_(bf_hi(g.z)); v[6] *= sigmoidf_(bf_lo(g.w)); v[7] *= sigmoidf_(bf_hi(g.w)); }
;                     u32x4 w; w.x = pkh(v[0], v[1]); w.y = pkh(v[2], v[3]); w.z = pkh(v[4], v[5]); w.w = pkh(v[6], v[7]);
;                     *(u32x4*)(ob + (size_t)row * LDC + col) = w; }
.LBB0_65:
	s_and_b64 vcc, exec, s[34:35]
	s_cbranch_vccz .LBB0_67
	v_mov_b32_e32 v0, v210
	s_lshl_b32 s2, s53, 8
	v_and_or_b32 v2, v0, 15, s49
	v_lshrrev_b32_e32 v0, 1, v0
	v_lshl_add_u32 v2, s54, 8, v2
	v_and_or_b32 v0, v0, 24, s2
	v_or_b32_e32 v136, s50, v0
	v_ashrrev_i32_e32 v3, 31, v2
	v_lshlrev_b64 v[138:139], 12, v[2:3]
	v_ashrrev_i32_e32 v137, 31, v136
	v_lshl_add_u64 v[138:139], s[10:11], 0, v[138:139]
	v_lshlrev_b64 v[136:137], 1, v[136:137]
	v_cvt_pk_bf16_f32 v132, v116, v117
	v_cvt_pk_bf16_f32 v133, v118, v119
	v_cvt_pk_bf16_f32 v134, v120, v121
	v_cvt_pk_bf16_f32 v135, v122, v123
	v_lshl_add_u64 v[138:139], v[138:139], 0, v[136:137]
	global_store_dwordx4 v[138:139], v[132:135], off sc1
	s_nop 1
	v_cvt_pk_bf16_f32 v132, v124, v125
	v_cvt_pk_bf16_f32 v133, v126, v127
	v_cvt_pk_bf16_f32 v134, v128, v129
	v_cvt_pk_bf16_f32 v135, v130, v131
	global_store_dwordx4 v[138:139], v[132:135], off offset:256 sc1
	v_or_b32_e32 v138, 16, v2
	v_ashrrev_i32_e32 v139, 31, v138
	v_lshlrev_b64 v[138:139], 12, v[138:139]
	v_lshl_add_u64 v[138:139], s[10:11], 0, v[138:139]
	v_cvt_pk_bf16_f32 v132, v100, v101
	v_cvt_pk_bf16_f32 v133, v102, v103
	v_cvt_pk_bf16_f32 v134, v104, v105
	v_cvt_pk_bf16_f32 v135, v106, v107
	v_lshl_add_u64 v[138:139], v[138:139], 0, v[136:137]
	global_store_dwordx4 v[138:139], v[132:135], off sc1
	s_nop 1
	v_cvt_pk_bf16_f32 v132, v108, v109
	v_cvt_pk_bf16_f32 v133, v110, v111
	v_cvt_pk_bf16_f32 v134, v112, v113
	v_cvt_pk_bf16_f32 v135, v114, v115
	global_store_dwordx4 v[138:139], v[132:135], off offset:256 sc1
	v_or_b32_e32 v138, 32, v2
	v_ashrrev_i32_e32 v139, 31, v138
	v_lshlrev_b64 v[138:139], 12, v[138:139]
	v_lshl_add_u64 v[138:139], s[10:11], 0, v[138:139]
	v_cvt_pk_bf16_f32 v132, v76, v77
	v_cvt_pk_bf16_f32 v133, v78, v79
	v_cvt_pk_bf16_f32 v134, v80, v81
	v_cvt_pk_bf16_f32 v135, v82, v83
	v_lshl_add_u64 v[138:139], v[138:139], 0, v[136:137]
	global_store_dwordx4 v[138:139], v[132:135], off sc1
	s_nop 1
	v_cvt_pk_bf16_f32 v132, v92, v93
	v_cvt_pk_bf16_f32 v133, v94, v95
	v_cvt_pk_bf16_f32 v134, v96, v97
	v_cvt_pk_bf16_f32 v135, v98, v99
	global_store_dwordx4 v[138:139], v[132:135], off offset:256 sc1
	v_or_b32_e32 v138, 48, v2
	v_ashrrev_i32_e32 v139, 31, v138
	v_lshlrev_b64 v[138:139], 12, v[138:139]
	v_lshl_add_u64 v[138:139], s[10:11], 0, v[138:139]
	v_cvt_pk_bf16_f32 v132, v44, v45
	v_cvt_pk_bf16_f32 v133, v46, v47
	v_cvt_pk_bf16_f32 v134, v48, v49
	v_cvt_pk_bf16_f32 v135, v50, v51
	v_lshl_add_u64 v[138:139], v[138:139], 0, v[136:137]
	global_store_dwordx4 v[138:139], v[132:135], off sc1
	s_nop 1
	v_cvt_pk_bf16_f32 v132, v68, v69
	v_cvt_pk_bf16_f32 v133, v70, v71
	v_cvt_pk_bf16_f32 v134, v72, v73
	v_cvt_pk_bf16_f32 v135, v74, v75
	global_store_dwordx4 v[138:139], v[132:135], off offset:256 sc1
	v_add_u32_e32 v138, 0x80, v2
	v_ashrrev_i32_e32 v139, 31, v138
	v_lshlrev_b64 v[138:139], 12, v[138:139]
	v_lshl_add_u64 v[138:139], s[10:11], 0, v[138:139]
	v_cvt_pk_bf16_f32 v132, v60, v61
	v_cvt_pk_bf16_f32 v133, v62, v63
	v_cvt_pk_bf16_f32 v134, v64, v65
	v_cvt_pk_bf16_f32 v135, v66, v67
	v_lshl_add_u64 v[138:139], v[138:139], 0, v[136:137]
	global_store_dwordx4 v[138:139], v[132:135], off sc1
	s_nop 1
	v_cvt_pk_bf16_f32 v132, v84, v85
	v_cvt_pk_bf16_f32 v133, v86, v87
	v_cvt_pk_bf16_f32 v134, v88, v89
	v_cvt_pk_bf16_f32 v135, v90, v91
	global_store_dwordx4 v[138:139], v[132:135], off offset:256 sc1
	v_add_u32_e32 v138, 0x90, v2
	v_ashrrev_i32_e32 v139, 31, v138
	v_lshlrev_b64 v[138:139], 12, v[138:139]
	v_lshl_add_u64 v[138:139], s[10:11], 0, v[138:139]
	v_cvt_pk_bf16_f32 v132, v36, v37
	v_cvt_pk_bf16_f32 v133, v38, v39
	v_cvt_pk_bf16_f32 v134, v40, v41
	v_cvt_pk_bf16_f32 v135, v42, v43
	v_lshl_add_u64 v[138:139], v[138:139], 0, v[136:137]
	global_store_dwordx4 v[138:139], v[132:135], off sc1
	s_nop 1
	v_cvt_pk_bf16_f32 v132, v52, v53
	v_cvt_pk_bf16_f32 v133, v54, v55
	v_cvt_pk_bf16_f32 v134, v56, v57
	v_cvt_pk_bf16_f32 v135, v58, v59
	global_store_dwordx4 v[138:139], v[132:135], off offset:256 sc1
	v_add_u32_e32 v138, 0xa0, v2
	v_ashrrev_i32_e32 v139, 31, v138
	v_lshlrev_b64 v[138:139], 12, v[138:139]
	v_add_u32_e32 v2, 0xb0, v2
	v_lshl_add_u64 v[138:139], s[10:11], 0, v[138:139]
	v_ashrrev_i32_e32 v3, 31, v2
	v_cvt_pk_bf16_f32 v132, v20, v21
	v_cvt_pk_bf16_f32 v133, v22, v23
	v_cvt_pk_bf16_f32 v134, v24, v25
	v_cvt_pk_bf16_f32 v135, v26, v27
	v_lshl_add_u64 v[138:139], v[138:139], 0, v[136:137]
	v_lshlrev_b64 v[2:3], 12, v[2:3]
	global_store_dwordx4 v[138:139], v[132:135], off sc1
	v_lshl_add_u64 v[2:3], s[10:11], 0, v[2:3]
	v_lshl_add_u64 v[2:3], v[2:3], 0, v[136:137]
	v_cvt_pk_bf16_f32 v132, v28, v29
	v_cvt_pk_bf16_f32 v133, v30, v31
	v_cvt_pk_bf16_f32 v134, v32, v33
	v_cvt_pk_bf16_f32 v135, v34, v35
	global_store_dwordx4 v[138:139], v[132:135], off offset:256 sc1
	s_nop 1
	v_cvt_pk_bf16_f32 v132, v4, v5
	v_cvt_pk_bf16_f32 v133, v6, v7
	v_cvt_pk_bf16_f32 v134, v8, v9
	v_cvt_pk_bf16_f32 v135, v10, v11
	global_store_dwordx4 v[2:3], v[132:135], off sc1
	s_nop 1
	v_cvt_pk_bf16_f32 v132, v12, v13
	v_cvt_pk_bf16_f32 v133, v14, v15
	v_cvt_pk_bf16_f32 v134, v16, v17
	v_cvt_pk_bf16_f32 v135, v18, v19
	global_store_dwordx4 v[2:3], v[132:135], off offset:256 sc1

; __device__ __forceinline__ float bf_lo(unsigned w) { return __uint_as_float(w << 16); }
; __device__ __forceinline__ float bf_hi(unsigned w) { return __uint_as_float(w & 0xffff0000u); }
; __device__ __forceinline__ float sigmoidf_(float x) { return 1.0f / (1.0f + __expf(-x)); }
;     template <int MODE> __device__ __forceinline__ void run(const pg8::f32x4 (&acc)[2][2][4][2], const pg8::Unit& u, int wr, int wc, int fr, int fq) const {
;     ...
;                 if constexpr (MODE == 6) {
; #pragma unroll
;                     for (int q = 0; q < 4; ++q) { const int m = 2 * mp + (q >> 1), bj = q & 1; const int row = u.pm * 256 + ai * 128 + wr * 64 + m * 16 + fr, col = u.pn * 256 + bj * 128 + wc * 32 + 8 * fq;
;                         gpre[q] = *(const u32x4*)(proj + (size_t)row * NP + OFF_MG + 2 * DM + col); }
;                 }
; #pragma unroll
;                 for (int q = 0; q < 4; ++q) { const int m = 2 * mp + (q >> 1), bj = q & 1; const int row = u.pm * 256 + ai * 128 + wr * 64 + m * 16 + fr, col = u.pn * 256 + bj * 128 + wc * 32 + 8 * fq;
;                     const pg8::f32x4 t0 = acc[ai][bj][m][0], t1 = acc[ai][bj][m][1];
;                     float v[8] = {t0[0], t0[1], t0[2], t0[3], t1[0], t1[1], t1[2], t1[3]};
;                     if constexpr (MODE == 5) {
; #pragma unroll
;                         for (int e = 0; e < 8; ++e) { const float r = fmaxf(v[e], 0.f); v[e] = r * r; }
;                     }
;                     if constexpr (MODE == 6) { const u32x4 g = gpre[q];
;                         v[0] *= sigmoidf_(bf_lo(g.x)); v[1] *= sigmoidf_(bf_hi(g.x)); v[2] *= sigmoidf_(bf_lo(g.y)); v[3] *= sigmoidf_(bf_hi(g.y));
;                         v[4] *= sigmoidf_(bf_lo(g.z)); v[5] *= sigmoidf_(bf_hi(g.z)); v[6] *= sigmoidf_(bf_lo(g.w)); v[7] *= sigmoidf_(bf_hi(g.w)); }
.LBB0_69:
	v_mov_b32_e32 v0, v210
	s_lshl_b32 s2, s53, 8
	v_and_or_b32 v2, v0, 15, s49
	v_lshrrev_b32_e32 v0, 1, v0
	v_and_or_b32 v0, v0, 24, s2
	v_lshl_add_u32 v148, s54, 8, v2
	v_or_b32_e32 v132, s50, v0
	v_mov_b64_e32 v[150:151], s[6:7]
	v_mad_i64_i32 v[2:3], s[28:29], v148, s76, v[150:151]
	s_mov_b64 s[30:31], 0x6a60
	v_ashrrev_i32_e32 v133, 31, v132
	v_lshl_add_u64 v[134:135], v[2:3], 0, s[30:31]
	v_lshlrev_b64 v[2:3], 1, v[132:133]
	v_lshl_add_u64 v[136:137], v[134:135], 0, v[2:3]
	global_load_dwordx4 v[144:147], v[136:137], off
	v_or_b32_e32 v132, 0x80, v132
	v_ashrrev_i32_e32 v133, 31, v132
	v_lshlrev_b64 v[152:153], 1, v[132:133]
	v_lshl_add_u64 v[132:133], v[134:135], 0, v[152:153]
	global_load_dwordx4 v[140:143], v[132:133], off
	v_ashrrev_i32_e32 v149, 31, v148
	v_or_b32_e32 v154, 16, v148
	v_mad_i64_i32 v[132:133], s[28:29], v154, s76, v[150:151]
	v_lshl_add_u64 v[132:133], v[132:133], 0, s[30:31]
	v_lshl_add_u64 v[134:135], v[132:133], 0, v[2:3]
	v_lshl_add_u64 v[132:133], v[132:133], 0, v[152:153]
	global_load_dwordx4 v[136:139], v[134:135], off
	v_ashrrev_i32_e32 v155, 31, v154
	global_load_dwordx4 v[132:135], v[132:133], off
	s_waitcnt vmcnt(0)
	v_lshlrev_b32_e32 v0, 16, v144
	v_mul_f32_e32 v0, 0xbfb8aa3b, v0
	v_exp_f32_e32 v156, v0
	v_and_b32_e32 v0, 0xffff0000, v144
	v_mul_f32_e32 v0, 0xbfb8aa3b, v0
	v_exp_f32_e32 v157, v0
	s_nop 0
	v_pk_add_f32 v[156:157], v[156:157], 1.0 op_sel_hi:[1,0]
	s_nop 0
	v_div_scale_f32 v0, s[28:29], v157, v157, 1.0
	v_rcp_f32_e32 v144, v0
	s_nop 0
	v_fma_f32 v158, -v0, v144, 1.0
	v_fmac_f32_e32 v144, v158, v144
	v_div_scale_f32 v158, vcc, 1.0, v157, 1.0
	v_mul_f32_e32 v159, v158, v144
	v_fma_f32 v160, -v0, v159, v158
	v_fmac_f32_e32 v159, v160, v144
	v_fma_f32 v0, -v0, v159, v158
	v_div_fmas_f32 v0, v0, v144, v159
	v_div_fixup_f32 v157, v0, v157, 1.0
	v_div_scale_f32 v0, s[28:29], v156, v156, 1.0
	v_rcp_f32_e32 v144, v0
	s_nop 0
	v_fma_f32 v158, -v0, v144, 1.0
	v_fmac_f32_e32 v144, v158, v144
	v_div_scale_f32 v158, vcc, 1.0, v156, 1.0
	v_mul_f32_e32 v159, v158, v144
	v_fma_f32 v160, -v0, v159, v158
	v_fmac_f32_e32 v159, v160, v144
	v_fma_f32 v0, -v0, v159, v158
	v_div_fmas_f32 v0, v0, v144, v159
	v_div_fixup_f32 v156, v0, v156, 1.0
	v_lshlrev_b32_e32 v0, 16, v145
	v_mul_f32_e32 v0, 0xbfb8aa3b, v0
	v_exp_f32_e32 v144, v0
	v_and_b32_e32 v0, 0xffff0000, v145
	v_mul_f32_e32 v0, 0xbfb8aa3b, v0
	v_exp_f32_e32 v145, v0
	v_pk_mul_f32 v[156:157], v[116:117], v[156:157]
	v_pk_add_f32 v[144:145], v[144:145], 1.0 op_sel_hi:[1,0]
	s_nop 0
	v_div_scale_f32 v0, s[28:29], v145, v145, 1.0
	v_rcp_f32_e32 v158, v0
	v_cvt_pk_bf16_f32 v156, v156, v157
	v_fma_f32 v159, -v0, v158, 1.0
	v_fmac_f32_e32 v158, v159, v158
	v_div_scale_f32 v159, vcc, 1.0, v145, 1.0
	v_mul_f32_e32 v160, v159, v158
	v_fma_f32 v161, -v0, v160, v159
	v_fmac_f32_e32 v160, v161, v158
	v_fma_f32 v0, -v0, v160, v159
	v_div_fmas_f32 v0, v0, v158, v160
	v_div_fixup_f32 v145, v0, v145, 1.0
	v_div_scale_f32 v0, s[28:29], v144, v144, 1.0
	v_rcp_f32_e32 v158, v0
	s_nop 0
	v_fma_f32 v159, -v0, v158, 1.0
	v_fmac_f32_e32 v158, v159, v158
	v_div_scale_f32 v159, vcc, 1.0, v144, 1.0
	v_mul_f32_e32 v160, v159, v158
	v_fma_f32 v161, -v0, v160, v159
	v_fmac_f32_e32 v160, v161, v158
	v_fma_f32 v0, -v0, v160, v159
	v_div_fmas_f32 v0, v0, v158, v160
	v_div_fixup_f32 v144, v0, v144, 1.0
	v_lshlrev_b32_e32 v0, 16, v146
	v_mul_f32_e32 v0, 0xbfb8aa3b, v0
	v_exp_f32_e32 v158, v0
	v_and_b32_e32 v0, 0xffff0000, v146
	v_mul_f32_e32 v0, 0xbfb8aa3b, v0
	v_exp_f32_e32 v159, v0
	v_pk_mul_f32 v[144:145], v[118:119], v[144:145]
	v_pk_add_f32 v[158:159], v[158:159], 1.0 op_sel_hi:[1,0]
	s_nop 0
	v_div_scale_f32 v0, s[28:29], v159, v159, 1.0
	v_rcp_f32_e32 v146, v0
	v_cvt_pk_bf16_f32 v157, v144, v145
	v_lshlrev_b64 v[144:145], 12, v[148:149]
	v_lshl_add_u64 v[144:145], s[10:11], 0, v[144:145]
	v_fma_f32 v160, -v0, v146, 1.0
	v_fmac_f32_e32 v146, v160, v146
	v_div_scale_f32 v160, vcc, 1.0, v159, 1.0
	v_mul_f32_e32 v161, v160, v146
	v_fma_f32 v162, -v0, v161, v160
	v_fmac_f32_e32 v161, v162, v146
	v_fma_f32 v0, -v0, v161, v160
	v_div_fmas_f32 v0, v0, v146, v161
	v_div_fixup_f32 v159, v0, v159, 1.0
	v_div_scale_f32 v0, s[28:29], v158, v158, 1.0
	v_rcp_f32_e32 v146, v0
	v_lshl_add_u64 v[144:145], v[144:145], 0, v[2:3]
	v_fma_f32 v160, -v0, v146, 1.0
	v_fmac_f32_e32 v146, v160, v146
	v_div_scale_f32 v160, vcc, 1.0, v158, 1.0
	v_mul_f32_e32 v161, v160, v146
	v_fma_f32 v162, -v0, v161, v160
	v_fmac_f32_e32 v161, v162, v146
	v_fma_f32 v0, -v0, v161, v160
	v_div_fmas_f32 v0, v0, v146, v161
	v_div_fixup_f32 v158, v0, v158, 1.0
	v_lshlrev_b32_e32 v0, 16, v147
	v_mul_f32_e32 v0, 0xbfb8aa3b, v0
	v_exp_f32_e32 v146, v0
	v_and_b32_e32 v0, 0xffff0000, v147
	v_mul_f32_e32 v0, 0xbfb8aa3b, v0
	v_exp_f32_e32 v147, v0
	v_pk_mul_f32 v[158:159], v[120:121], v[158:159]
	v_pk_add_f32 v[146:147], v[146:147], 1.0 op_sel_hi:[1,0]
	s_nop 0
	v_div_scale_f32 v0, s[28:29], v147, v147, 1.0
	v_rcp_f32_e32 v160, v0
	v_cvt_pk_bf16_f32 v158, v158, v159
	v_fma_f32 v161, -v0, v160, 1.0
	v_fmac_f32_e32 v160, v161, v160
	v_div_scale_f32 v161, vcc, 1.0, v147, 1.0
	v_mul_f32_e32 v162, v161, v160
	v_fma_f32 v163, -v0, v162, v161
	v_fmac_f32_e32 v162, v163, v160
	v_fma_f32 v0, -v0, v162, v161
	v_div_fmas_f32 v0, v0, v160, v162
	v_div_fixup_f32 v147, v0, v147, 1.0
	v_div_scale_f32 v0, s[28:29], v146, v146, 1.0
	v_rcp_f32_e32 v160, v0
	s_nop 0
	v_fma_f32 v161, -v0, v160, 1.0
	v_fmac_f32_e32 v160, v161, v160
	v_div_scale_f32 v161, vcc, 1.0, v146, 1.0
	v_mul_f32_e32 v162, v161, v160
	v_fma_f32 v163, -v0, v162, v161
	v_fmac_f32_e32 v162, v163, v160
	v_fma_f32 v0, -v0, v162, v161
	v_div_fmas_f32 v0, v0, v160, v162
; __device__ __forceinline__ unsigned pkh(float lo, float hi) { f32v2_t v; v.x = lo; v.y = hi; return __builtin_bit_cast(unsigned, __builtin_convertvector(v, bf16v2_t)); }
; __device__ __forceinline__ float bf_lo(unsigned w) { return __uint_as_float(w << 16); }
; __device__ __forceinline__ float bf_hi(unsigned w) { return __uint_as_float(w & 0xffff0000u); }
; __device__ __forceinline__ float sigmoidf_(float x) { return 1.0f / (1.0f + __expf(-x)); }
;     template <int MODE> __device__ __forceinline__ void run(const pg8::f32x4 (&acc)[2][2][4][2], const pg8::Unit& u, int wr, int wc, int fr, int fq) const {
;     ...
;                     if constexpr (MODE == 6) { const u32x4 g = gpre[q];
;                         v[0] *= sigmoidf_(bf_lo(g.x)); v[1] *= sigmoidf_(bf_hi(g.x)); v[2] *= sigmoidf_(bf_lo(g.y)); v[3] *= sigmoidf_(bf_hi(g.y));
;                         v[4] *= sigmoidf_(bf_lo(g.z)); v[5] *= sigmoidf_(bf_hi(g.z)); v[6] *= sigmoidf_(bf_lo(g.w)); v[7] *= sigmoidf_(bf_hi(g.w)); }
;                     u32x4 w; w.x = pkh(v[0], v[1]); w.y = pkh(v[2], v[3]); w.z = pkh(v[4], v[5]); w.w = pkh(v[6], v[7]);
;                     *(u32x4*)(ob + (size_t)row * LDC + col) = w; }
	v_div_fixup_f32 v146, v0, v146, 1.0
	v_lshlrev_b32_e32 v0, 16, v140
	v_pk_mul_f32 v[146:147], v[122:123], v[146:147]
	v_mul_f32_e32 v0, 0xbfb8aa3b, v0
	v_cvt_pk_bf16_f32 v159, v146, v147
	v_exp_f32_e32 v146, v0
	v_and_b32_e32 v0, 0xffff0000, v140
	v_mul_f32_e32 v0, 0xbfb8aa3b, v0
	v_exp_f32_e32 v147, v0
	global_store_dwordx4 v[144:145], v[156:159], off sc1
	v_pk_add_f32 v[146:147], v[146:147], 1.0 op_sel_hi:[1,0]
	s_nop 0
	v_div_scale_f32 v0, s[28:29], v147, v147, 1.0
	v_rcp_f32_e32 v140, v0
	s_nop 0
	v_fma_f32 v149, -v0, v140, 1.0
	v_fmac_f32_e32 v140, v149, v140
	v_div_scale_f32 v149, vcc, 1.0, v147, 1.0
	v_mul_f32_e32 v156, v149, v140
	v_fma_f32 v157, -v0, v156, v149
	v_fmac_f32_e32 v156, v157, v140
	v_fma_f32 v0, -v0, v156, v149
	v_div_fmas_f32 v0, v0, v140, v156
	v_div_fixup_f32 v147, v0, v147, 1.0
	v_div_scale_f32 v0, s[28:29], v146, v146, 1.0
	v_rcp_f32_e32 v140, v0
	s_nop 0
	v_fma_f32 v149, -v0, v140, 1.0
	v_fmac_f32_e32 v140, v149, v140
	v_div_scale_f32 v149, vcc, 1.0, v146, 1.0
	v_mul_f32_e32 v156, v149, v140
	v_fma_f32 v157, -v0, v156, v149
	v_fmac_f32_e32 v156, v157, v140
	v_fma_f32 v0, -v0, v156, v149
	v_div_fmas_f32 v0, v0, v140, v156
	v_div_fixup_f32 v146, v0, v146, 1.0
	v_lshlrev_b32_e32 v0, 16, v141
	v_mul_f32_e32 v0, 0xbfb8aa3b, v0
	v_exp_f32_e32 v140, v0
	v_and_b32_e32 v0, 0xffff0000, v141
	v_mul_f32_e32 v0, 0xbfb8aa3b, v0
	v_exp_f32_e32 v141, v0
	v_pk_mul_f32 v[146:147], v[124:125], v[146:147]
	v_pk_add_f32 v[140:141], v[140:141], 1.0 op_sel_hi:[1,0]
	s_nop 0
	v_div_scale_f32 v0, s[28:29], v141, v141, 1.0
	v_rcp_f32_e32 v149, v0
	s_nop 0
	v_fma_f32 v156, -v0, v149, 1.0
	v_fmac_f32_e32 v149, v156, v149
	v_div_scale_f32 v156, vcc, 1.0, v141, 1.0
	v_mul_f32_e32 v157, v156, v149
	v_fma_f32 v158, -v0, v157, v156
	v_fmac_f32_e32 v157, v158, v149
	v_fma_f32 v0, -v0, v157, v156
	v_div_fmas_f32 v0, v0, v149, v157
	v_div_fixup_f32 v141, v0, v141, 1.0
	v_div_scale_f32 v0, s[28:29], v140, v140, 1.0
	v_rcp_f32_e32 v149, v0
	s_nop 0
	v_fma_f32 v156, -v0, v149, 1.0
	v_fmac_f32_e32 v149, v156, v149
	v_div_scale_f32 v156, vcc, 1.0, v140, 1.0
	v_mul_f32_e32 v157, v156, v149
	v_fma_f32 v158, -v0, v157, v156
	v_fmac_f32_e32 v157, v158, v149
	v_fma_f32 v0, -v0, v157, v156
	v_div_fmas_f32 v0, v0, v149, v157
	v_div_fixup_f32 v140, v0, v140, 1.0
	v_lshlrev_b32_e32 v0, 16, v142
	v_mul_f32_e32 v0, 0xbfb8aa3b, v0
	v_pk_mul_f32 v[156:157], v[126:127], v[140:141]
	v_exp_f32_e32 v140, v0
	v_and_b32_e32 v0, 0xffff0000, v142
	v_mul_f32_e32 v0, 0xbfb8aa3b, v0
	v_exp_f32_e32 v141, v0
	s_nop 0
	v_pk_add_f32 v[140:141], v[140:141], 1.0 op_sel_hi:[1,0]
	s_nop 0
	v_div_scale_f32 v0, s[28:29], v141, v141, 1.0
	v_rcp_f32_e32 v142, v0
	s_nop 0
	v_fma_f32 v149, -v0, v142, 1.0
	v_fmac_f32_e32 v142, v149, v142
	v_div_scale_f32 v149, vcc, 1.0, v141, 1.0
	v_mul_f32_e32 v158, v149, v142
	v_fma_f32 v159, -v0, v158, v149
	v_fmac_f32_e32 v158, v159, v142
	v_fma_f32 v0, -v0, v158, v149
	v_div_fmas_f32 v0, v0, v142, v158
	v_div_fixup_f32 v141, v0, v141, 1.0
	v_div_scale_f32 v0, s[28:29], v140, v140, 1.0
	v_rcp_f32_e32 v142, v0
	s_nop 0
	v_fma_f32 v149, -v0, v142, 1.0
	v_fmac_f32_e32 v142, v149, v142
	v_div_scale_f32 v149, vcc, 1.0, v140, 1.0
	v_mul_f32_e32 v158, v149, v142
	v_fma_f32 v159, -v0, v158, v149
	v_fmac_f32_e32 v158, v159, v142
	v_fma_f32 v0, -v0, v158, v149
	v_div_fmas_f32 v0, v0, v142, v158
	v_div_fixup_f32 v140, v0, v140, 1.0
	v_lshlrev_b32_e32 v0, 16, v143
	v_mul_f32_e32 v0, 0xbfb8aa3b, v0
	v_pk_mul_f32 v[158:159], v[128:129], v[140:141]
	v_exp_f32_e32 v140, v0
	v_and_b32_e32 v0, 0xffff0000, v143
	v_mul_f32_e32 v0, 0xbfb8aa3b, v0
	v_exp_f32_e32 v141, v0
	s_nop 0
	v_pk_add_f32 v[140:141], v[140:141], 1.0 op_sel_hi:[1,0]
	s_nop 0
	v_div_scale_f32 v0, s[28:29], v141, v141, 1.0
	v_rcp_f32_e32 v142, v0
	s_nop 0
	v_fma_f32 v143, -v0, v142, 1.0
	v_fmac_f32_e32 v142, v143, v142
	v_div_scale_f32 v143, vcc, 1.0, v141, 1.0
	v_mul_f32_e32 v149, v143, v142
	v_fma_f32 v160, -v0, v149, v143
	v_fmac_f32_e32 v149, v160, v142
	v_fma_f32 v0, -v0, v149, v143
	v_div_fmas_f32 v0, v0, v142, v149
	v_div_fixup_f32 v141, v0, v141, 1.0
	v_div_scale_f32 v0, s[28:29], v140, v140, 1.0
	v_rcp_f32_e32 v142, v0
	s_nop 0
	v_fma_f32 v143, -v0, v142, 1.0
	v_fmac_f32_e32 v142, v143, v142
	v_div_scale_f32 v143, vcc, 1.0, v140, 1.0
	v_mul_f32_e32 v149, v143, v142
	v_fma_f32 v160, -v0, v149, v143
	v_fmac_f32_e32 v149, v160, v142
	v_fma_f32 v0, -v0, v149, v143
	v_div_fmas_f32 v0, v0, v142, v149
	v_div_fixup_f32 v140, v0, v140, 1.0
	v_pk_mul_f32 v[160:161], v[130:131], v[140:141]
	v_lshlrev_b32_e32 v0, 16, v136
	v_cvt_pk_bf16_f32 v140, v146, v147
	v_cvt_pk_bf16_f32 v141, v156, v157
	v_cvt_pk_bf16_f32 v142, v158, v159
	v_cvt_pk_bf16_f32 v143, v160, v161
	v_mul_f32_e32 v0, 0xbfb8aa3b, v0
	global_store_dwordx4 v[144:145], v[140:143], off offset:256 sc1
	s_nop 1
	v_exp_f32_e32 v140, v0
	v_and_b32_e32 v0, 0xffff0000, v136
	v_mul_f32_e32 v0, 0xbfb8aa3b, v0
	v_exp_f32_e32 v141, v0
	s_nop 0
	v_pk_add_f32 v[140:141], v[140:141], 1.0 op_sel_hi:[1,0]
	s_nop 0
	v_div_scale_f32 v0, s[28:29], v141, v141, 1.0
	v_rcp_f32_e32 v136, v0
	s_nop 0
	v_fma_f32 v142, -v0, v136, 1.0
	v_fmac_f32_e32 v136, v142, v136
	v_div_scale_f32 v142, vcc, 1.0, v141, 1.0
	v_mul_f32_e32 v143, v142, v136
	v_fma_f32 v144, -v0, v143, v142
	v_fmac_f32_e32 v143, v144, v136
	v_fma_f32 v0, -v0, v143, v142
	v_div_fmas_f32 v0, v0, v136, v143
	v_div_fixup_f32 v141, v0, v141, 1.0
	v_div_scale_f32 v0, s[28:29], v140, v140, 1.0
	v_rcp_f32_e32 v136, v0
	s_nop 0
	v_fma_f32 v142, -v0, v136, 1.0
	v_fmac_f32_e32 v136, v142, v136
	v_div_scale_f32 v142, vcc, 1.0, v140, 1.0
	v_mul_f32_e32 v143, v142, v136
	v_fma_f32 v144, -v0, v143, v142
; __device__ __forceinline__ unsigned pkh(float lo, float hi) { f32v2_t v; v.x = lo; v.y = hi; return __builtin_bit_cast(unsigned, __builtin_convertvector(v, bf16v2_t)); }
; __device__ __forceinline__ float bf_lo(unsigned w) { return __uint_as_float(w << 16); }
; __device__ __forceinline__ float bf_hi(unsigned w) { return __uint_as_float(w & 0xffff0000u); }
; __device__ __forceinline__ float sigmoidf_(float x) { return 1.0f / (1.0f + __expf(-x)); }
;     template <int MODE> __device__ __forceinline__ void run(const pg8::f32x4 (&acc)[2][2][4][2], const pg8::Unit& u, int wr, int wc, int fr, int fq) const {
;     ...
;                     if constexpr (MODE == 6) { const u32x4 g = gpre[q];
;                         v[0] *= sigmoidf_(bf_lo(g.x)); v[1] *= sigmoidf_(bf_hi(g.x)); v[2] *= sigmoidf_(bf_lo(g.y)); v[3] *= sigmoidf_(bf_hi(g.y));
;                         v[4] *= sigmoidf_(bf_lo(g.z)); v[5] *= sigmoidf_(bf_hi(g.z)); v[6] *= sigmoidf_(bf_lo(g.w)); v[7] *= sigmoidf_(bf_hi(g.w)); }
;                     u32x4 w; w.x = pkh(v[0], v[1]); w.y = pkh(v[2], v[3]); w.z = pkh(v[4], v[5]); w.w = pkh(v[6], v[7]);
;                     *(u32x4*)(ob + (size_t)row * LDC + col) = w; }
	v_fmac_f32_e32 v143, v144, v136
	v_fma_f32 v0, -v0, v143, v142
	v_div_fmas_f32 v0, v0, v136, v143
	v_div_fixup_f32 v140, v0, v140, 1.0
	v_lshlrev_b32_e32 v0, 16, v137
	v_mul_f32_e32 v0, 0xbfb8aa3b, v0
	v_exp_f32_e32 v136, v0
	v_and_b32_e32 v0, 0xffff0000, v137
	v_mul_f32_e32 v0, 0xbfb8aa3b, v0
	v_exp_f32_e32 v137, v0
	v_pk_mul_f32 v[140:141], v[100:101], v[140:141]
	v_pk_add_f32 v[136:137], v[136:137], 1.0 op_sel_hi:[1,0]
	s_nop 0
	v_div_scale_f32 v0, s[28:29], v137, v137, 1.0
	v_rcp_f32_e32 v142, v0
	s_nop 0
	v_fma_f32 v143, -v0, v142, 1.0
	v_fmac_f32_e32 v142, v143, v142
	v_div_scale_f32 v143, vcc, 1.0, v137, 1.0
	v_mul_f32_e32 v144, v143, v142
	v_fma_f32 v145, -v0, v144, v143
	v_fmac_f32_e32 v144, v145, v142
	v_fma_f32 v0, -v0, v144, v143
	v_div_fmas_f32 v0, v0, v142, v144
	v_div_fixup_f32 v137, v0, v137, 1.0
	v_div_scale_f32 v0, s[28:29], v136, v136, 1.0
	v_rcp_f32_e32 v142, v0
	s_nop 0
	v_fma_f32 v143, -v0, v142, 1.0
	v_fmac_f32_e32 v142, v143, v142
	v_div_scale_f32 v143, vcc, 1.0, v136, 1.0
	v_mul_f32_e32 v144, v143, v142
	v_fma_f32 v145, -v0, v144, v143
	v_fmac_f32_e32 v144, v145, v142
	v_fma_f32 v0, -v0, v144, v143
	v_div_fmas_f32 v0, v0, v142, v144
	v_div_fixup_f32 v136, v0, v136, 1.0
	v_lshlrev_b32_e32 v0, 16, v138
	v_mul_f32_e32 v0, 0xbfb8aa3b, v0
	v_exp_f32_e32 v142, v0
	v_and_b32_e32 v0, 0xffff0000, v138
	v_mul_f32_e32 v0, 0xbfb8aa3b, v0
	v_exp_f32_e32 v143, v0
	v_pk_mul_f32 v[136:137], v[102:103], v[136:137]
	v_pk_add_f32 v[142:143], v[142:143], 1.0 op_sel_hi:[1,0]
	s_nop 0
	v_div_scale_f32 v0, s[28:29], v143, v143, 1.0
	v_rcp_f32_e32 v138, v0
	s_nop 0
	v_fma_f32 v144, -v0, v138, 1.0
	v_fmac_f32_e32 v138, v144, v138
	v_div_scale_f32 v144, vcc, 1.0, v143, 1.0
	v_mul_f32_e32 v145, v144, v138
	v_fma_f32 v146, -v0, v145, v144
	v_fmac_f32_e32 v145, v146, v138
	v_fma_f32 v0, -v0, v145, v144
	v_div_fmas_f32 v0, v0, v138, v145
	v_div_fixup_f32 v143, v0, v143, 1.0
	v_div_scale_f32 v0, s[28:29], v142, v142, 1.0
	v_rcp_f32_e32 v138, v0
	s_nop 0
	v_fma_f32 v144, -v0, v138, 1.0
	v_fmac_f32_e32 v138, v144, v138
	v_div_scale_f32 v144, vcc, 1.0, v142, 1.0
	v_mul_f32_e32 v145, v144, v138
	v_fma_f32 v146, -v0, v145, v144
	v_fmac_f32_e32 v145, v146, v138
	v_fma_f32 v0, -v0, v145, v144
	v_div_fmas_f32 v0, v0, v138, v145
	v_div_fixup_f32 v142, v0, v142, 1.0
	v_lshlrev_b32_e32 v0, 16, v139
	v_mul_f32_e32 v0, 0xbfb8aa3b, v0
	v_exp_f32_e32 v138, v0
	v_and_b32_e32 v0, 0xffff0000, v139
	v_mul_f32_e32 v0, 0xbfb8aa3b, v0
	v_exp_f32_e32 v139, v0
	v_pk_mul_f32 v[142:143], v[104:105], v[142:143]
	v_pk_add_f32 v[138:139], v[138:139], 1.0 op_sel_hi:[1,0]
	s_nop 0
	v_div_scale_f32 v0, s[28:29], v139, v139, 1.0
	v_rcp_f32_e32 v144, v0
	s_nop 0
	v_fma_f32 v145, -v0, v144, 1.0
	v_fmac_f32_e32 v144, v145, v144
	v_div_scale_f32 v145, vcc, 1.0, v139, 1.0
	v_mul_f32_e32 v146, v145, v144
	v_fma_f32 v147, -v0, v146, v145
	v_fmac_f32_e32 v146, v147, v144
	v_fma_f32 v0, -v0, v146, v145
	v_div_fmas_f32 v0, v0, v144, v146
	v_div_fixup_f32 v139, v0, v139, 1.0
	v_div_scale_f32 v0, s[28:29], v138, v138, 1.0
	v_rcp_f32_e32 v144, v0
	s_nop 0
	v_fma_f32 v145, -v0, v144, 1.0
	v_fmac_f32_e32 v144, v145, v144
	v_div_scale_f32 v145, vcc, 1.0, v138, 1.0
	v_mul_f32_e32 v146, v145, v144
	v_fma_f32 v147, -v0, v146, v145
	v_fmac_f32_e32 v146, v147, v144
	v_fma_f32 v0, -v0, v146, v145
	v_div_fmas_f32 v0, v0, v144, v146
	v_div_fixup_f32 v138, v0, v138, 1.0
	v_pk_mul_f32 v[144:145], v[106:107], v[138:139]
	v_cvt_pk_bf16_f32 v139, v136, v137
	v_lshlrev_b64 v[136:137], 12, v[154:155]
	v_lshl_add_u64 v[136:137], s[10:11], 0, v[136:137]
	v_lshlrev_b32_e32 v0, 16, v132
	v_cvt_pk_bf16_f32 v138, v140, v141
	v_cvt_pk_bf16_f32 v140, v142, v143
	v_cvt_pk_bf16_f32 v141, v144, v145
	v_lshl_add_u64 v[136:137], v[136:137], 0, v[2:3]
	v_mul_f32_e32 v0, 0xbfb8aa3b, v0
	global_store_dwordx4 v[136:137], v[138:141], off sc1
	v_add_u32_e32 v154, 32, v148
	v_ashrrev_i32_e32 v155, 31, v154
	v_exp_f32_e32 v138, v0
	v_and_b32_e32 v0, 0xffff0000, v132
	v_mul_f32_e32 v0, 0xbfb8aa3b, v0
	v_exp_f32_e32 v139, v0
	s_nop 0
	v_pk_add_f32 v[138:139], v[138:139], 1.0 op_sel_hi:[1,0]
	s_nop 0
	v_div_scale_f32 v0, s[28:29], v139, v139, 1.0
	v_rcp_f32_e32 v132, v0
	s_nop 0
	v_fma_f32 v140, -v0, v132, 1.0
	v_fmac_f32_e32 v132, v140, v132
	v_div_scale_f32 v140, vcc, 1.0, v139, 1.0
	v_mul_f32_e32 v141, v140, v132
	v_fma_f32 v142, -v0, v141, v140
	v_fmac_f32_e32 v141, v142, v132
	v_fma_f32 v0, -v0, v141, v140
	v_div_fmas_f32 v0, v0, v132, v141
	v_div_fixup_f32 v139, v0, v139, 1.0
	v_div_scale_f32 v0, s[28:29], v138, v138, 1.0
	v_rcp_f32_e32 v132, v0
	s_nop 0
	v_fma_f32 v140, -v0, v132, 1.0
	v_fmac_f32_e32 v132, v140, v132
	v_div_scale_f32 v140, vcc, 1.0, v138, 1.0
	v_mul_f32_e32 v141, v140, v132
	v_fma_f32 v142, -v0, v141, v140
	v_fmac_f32_e32 v141, v142, v132
	v_fma_f32 v0, -v0, v141, v140
	v_div_fmas_f32 v0, v0, v132, v141
	v_div_fixup_f32 v138, v0, v138, 1.0
	v_lshlrev_b32_e32 v0, 16, v133
	v_mul_f32_e32 v0, 0xbfb8aa3b, v0
	v_exp_f32_e32 v132, v0
	v_and_b32_e32 v0, 0xffff0000, v133
	v_mul_f32_e32 v0, 0xbfb8aa3b, v0
	v_exp_f32_e32 v133, v0
	v_pk_mul_f32 v[138:139], v[108:109], v[138:139]
	v_pk_add_f32 v[132:133], v[132:133], 1.0 op_sel_hi:[1,0]
	s_nop 0
	v_div_scale_f32 v0, s[28:29], v133, v133, 1.0
	v_rcp_f32_e32 v140, v0
	s_nop 0
	v_fma_f32 v141, -v0, v140, 1.0
	v_fmac_f32_e32 v140, v141, v140
	v_div_scale_f32 v141, vcc, 1.0, v133, 1.0
	v_mul_f32_e32 v142, v141, v140
	v_fma_f32 v143, -v0, v142, v141
	v_fmac_f32_e32 v142, v143, v140
	v_fma_f32 v0, -v0, v142, v141
	v_div_fmas_f32 v0, v0, v140, v142
	v_div_fixup_f32 v133, v0, v133, 1.0
	v_div_scale_f32 v0, s[28:29], v132, v132, 1.0
	v_rcp_f32_e32 v140, v0
	s_nop 0
; __device__ __forceinline__ unsigned pkh(float lo, float hi) { f32v2_t v; v.x = lo; v.y = hi; return __builtin_bit_cast(unsigned, __builtin_convertvector(v, bf16v2_t)); }
; __device__ __forceinline__ float bf_lo(unsigned w) { return __uint_as_float(w << 16); }
; __device__ __forceinline__ float bf_hi(unsigned w) { return __uint_as_float(w & 0xffff0000u); }
; __device__ __forceinline__ float sigmoidf_(float x) { return 1.0f / (1.0f + __expf(-x)); }
;     template <int MODE> __device__ __forceinline__ void run(const pg8::f32x4 (&acc)[2][2][4][2], const pg8::Unit& u, int wr, int wc, int fr, int fq) const {
;     ...
;                     for (int q = 0; q < 4; ++q) { const int m = 2 * mp + (q >> 1), bj = q & 1; const int row = u.pm * 256 + ai * 128 + wr * 64 + m * 16 + fr, col = u.pn * 256 + bj * 128 + wc * 32 + 8 * fq;
;                         gpre[q] = *(const u32x4*)(proj + (size_t)row * NP + OFF_MG + 2 * DM + col); }
;                 }
; #pragma unroll
;                 for (int q = 0; q < 4; ++q) { const int m = 2 * mp + (q >> 1), bj = q & 1; const int row = u.pm * 256 + ai * 128 + wr * 64 + m * 16 + fr, col = u.pn * 256 + bj * 128 + wc * 32 + 8 * fq;
;                     const pg8::f32x4 t0 = acc[ai][bj][m][0], t1 = acc[ai][bj][m][1];
;                     float v[8] = {t0[0], t0[1], t0[2], t0[3], t1[0], t1[1], t1[2], t1[3]};
;                     if constexpr (MODE == 5) {
; #pragma unroll
;                         for (int e = 0; e < 8; ++e) { const float r = fmaxf(v[e], 0.f); v[e] = r * r; }
;                     }
;                     if constexpr (MODE == 6) { const u32x4 g = gpre[q];
;                         v[0] *= sigmoidf_(bf_lo(g.x)); v[1] *= sigmoidf_(bf_hi(g.x)); v[2] *= sigmoidf_(bf_lo(g.y)); v[3] *= sigmoidf_(bf_hi(g.y));
;                         v[4] *= sigmoidf_(bf_lo(g.z)); v[5] *= sigmoidf_(bf_hi(g.z)); v[6] *= sigmoidf_(bf_lo(g.w)); v[7] *= sigmoidf_(bf_hi(g.w)); }
;                     u32x4 w; w.x = pkh(v[0], v[1]); w.y = pkh(v[2], v[3]); w.z = pkh(v[4], v[5]); w.w = pkh(v[6], v[7]);
;                     *(u32x4*)(ob + (size_t)row * LDC + col) = w; }
	v_fma_f32 v141, -v0, v140, 1.0
	v_fmac_f32_e32 v140, v141, v140
	v_div_scale_f32 v141, vcc, 1.0, v132, 1.0
	v_mul_f32_e32 v142, v141, v140
	v_fma_f32 v143, -v0, v142, v141
	v_fmac_f32_e32 v142, v143, v140
	v_fma_f32 v0, -v0, v142, v141
	v_div_fmas_f32 v0, v0, v140, v142
	v_div_fixup_f32 v132, v0, v132, 1.0
	v_lshlrev_b32_e32 v0, 16, v134
	v_mul_f32_e32 v0, 0xbfb8aa3b, v0
	v_pk_mul_f32 v[140:141], v[110:111], v[132:133]
	v_exp_f32_e32 v132, v0
	v_and_b32_e32 v0, 0xffff0000, v134
	v_mul_f32_e32 v0, 0xbfb8aa3b, v0
	v_exp_f32_e32 v133, v0
	s_nop 0
	v_pk_add_f32 v[132:133], v[132:133], 1.0 op_sel_hi:[1,0]
	s_nop 0
	v_div_scale_f32 v0, s[28:29], v133, v133, 1.0
	v_rcp_f32_e32 v134, v0
	s_nop 0
	v_fma_f32 v142, -v0, v134, 1.0
	v_fmac_f32_e32 v134, v142, v134
	v_div_scale_f32 v142, vcc, 1.0, v133, 1.0
	v_mul_f32_e32 v143, v142, v134
	v_fma_f32 v144, -v0, v143, v142
	v_fmac_f32_e32 v143, v144, v134
	v_fma_f32 v0, -v0, v143, v142
	v_div_fmas_f32 v0, v0, v134, v143
	v_div_fixup_f32 v133, v0, v133, 1.0
	v_div_scale_f32 v0, s[28:29], v132, v132, 1.0
	v_rcp_f32_e32 v134, v0
	s_nop 0
	v_fma_f32 v142, -v0, v134, 1.0
	v_fmac_f32_e32 v134, v142, v134
	v_div_scale_f32 v142, vcc, 1.0, v132, 1.0
	v_mul_f32_e32 v143, v142, v134
	v_fma_f32 v144, -v0, v143, v142
	v_fmac_f32_e32 v143, v144, v134
	v_fma_f32 v0, -v0, v143, v142
	v_div_fmas_f32 v0, v0, v134, v143
	v_div_fixup_f32 v132, v0, v132, 1.0
	v_lshlrev_b32_e32 v0, 16, v135
	v_mul_f32_e32 v0, 0xbfb8aa3b, v0
	v_pk_mul_f32 v[142:143], v[112:113], v[132:133]
	v_exp_f32_e32 v132, v0
	v_and_b32_e32 v0, 0xffff0000, v135
	v_mul_f32_e32 v0, 0xbfb8aa3b, v0
	v_exp_f32_e32 v133, v0
	s_nop 0
	v_pk_add_f32 v[132:133], v[132:133], 1.0 op_sel_hi:[1,0]
	s_nop 0
	v_div_scale_f32 v0, s[28:29], v133, v133, 1.0
	v_rcp_f32_e32 v134, v0
	s_nop 0
	v_fma_f32 v135, -v0, v134, 1.0
	v_fmac_f32_e32 v134, v135, v134
	v_div_scale_f32 v135, vcc, 1.0, v133, 1.0
	v_mul_f32_e32 v144, v135, v134
	v_fma_f32 v145, -v0, v144, v135
	v_fmac_f32_e32 v144, v145, v134
	v_fma_f32 v0, -v0, v144, v135
	v_div_fmas_f32 v0, v0, v134, v144
	v_div_fixup_f32 v133, v0, v133, 1.0
	v_div_scale_f32 v0, s[28:29], v132, v132, 1.0
	v_rcp_f32_e32 v134, v0
	s_nop 0
	v_fma_f32 v135, -v0, v134, 1.0
	v_fmac_f32_e32 v134, v135, v134
	v_div_scale_f32 v135, vcc, 1.0, v132, 1.0
	v_mul_f32_e32 v144, v135, v134
	v_fma_f32 v145, -v0, v144, v135
	v_fmac_f32_e32 v144, v145, v134
	v_fma_f32 v0, -v0, v144, v135
	v_div_fmas_f32 v0, v0, v134, v144
	v_div_fixup_f32 v132, v0, v132, 1.0
	v_pk_mul_f32 v[144:145], v[114:115], v[132:133]
	v_cvt_pk_bf16_f32 v132, v138, v139
	v_cvt_pk_bf16_f32 v133, v140, v141
	v_cvt_pk_bf16_f32 v134, v142, v143
	v_cvt_pk_bf16_f32 v135, v144, v145
	global_store_dwordx4 v[136:137], v[132:135], off offset:256 sc1
	v_add_u32_e32 v0, 48, v148
	s_nop 0
	v_mad_i64_i32 v[132:133], s[28:29], v154, s76, v[150:151]
	v_lshl_add_u64 v[132:133], v[132:133], 0, s[30:31]
	v_lshl_add_u64 v[134:135], v[132:133], 0, v[2:3]
	global_load_dwordx4 v[144:147], v[134:135], off
	v_lshl_add_u64 v[132:133], v[132:133], 0, v[152:153]
	global_load_dwordx4 v[140:143], v[132:133], off
	v_mad_i64_i32 v[132:133], s[28:29], v0, s76, v[150:151]
	v_lshl_add_u64 v[132:133], v[132:133], 0, s[30:31]
	v_lshl_add_u64 v[134:135], v[132:133], 0, v[2:3]
	v_lshl_add_u64 v[132:133], v[132:133], 0, v[152:153]
	global_load_dwordx4 v[136:139], v[134:135], off
	s_waitcnt vmcnt(0)
	v_lshlrev_b32_e32 v0, 16, v144
	v_mul_f32_e32 v0, 0xbfb8aa3b, v0
	v_exp_f32_e32 v156, v0
	v_and_b32_e32 v0, 0xffff0000, v144
	v_mul_f32_e32 v0, 0xbfb8aa3b, v0
	v_exp_f32_e32 v157, v0
	global_load_dwordx4 v[132:135], v[132:133], off
	v_pk_add_f32 v[156:157], v[156:157], 1.0 op_sel_hi:[1,0]
	s_nop 0
	v_div_scale_f32 v0, s[28:29], v157, v157, 1.0
	v_rcp_f32_e32 v144, v0
	s_nop 0
	v_fma_f32 v149, -v0, v144, 1.0
	v_fmac_f32_e32 v144, v149, v144
	v_div_scale_f32 v149, vcc, 1.0, v157, 1.0
	v_mul_f32_e32 v158, v149, v144
	v_fma_f32 v159, -v0, v158, v149
	v_fmac_f32_e32 v158, v159, v144
	v_fma_f32 v0, -v0, v158, v149
	v_div_fmas_f32 v0, v0, v144, v158
	v_div_fixup_f32 v157, v0, v157, 1.0
	v_div_scale_f32 v0, s[28:29], v156, v156, 1.0
	v_rcp_f32_e32 v144, v0
	s_nop 0
	v_fma_f32 v149, -v0, v144, 1.0
	v_fmac_f32_e32 v144, v149, v144
	v_div_scale_f32 v149, vcc, 1.0, v156, 1.0
	v_mul_f32_e32 v158, v149, v144
	v_fma_f32 v159, -v0, v158, v149
	v_fmac_f32_e32 v158, v159, v144
	v_fma_f32 v0, -v0, v158, v149
	v_div_fmas_f32 v0, v0, v144, v158
	v_div_fixup_f32 v156, v0, v156, 1.0
	v_lshlrev_b32_e32 v0, 16, v145
	v_mul_f32_e32 v0, 0xbfb8aa3b, v0
	v_exp_f32_e32 v144, v0
	v_and_b32_e32 v0, 0xffff0000, v145
	v_mul_f32_e32 v0, 0xbfb8aa3b, v0
	v_exp_f32_e32 v145, v0
	v_pk_mul_f32 v[156:157], v[76:77], v[156:157]
	v_pk_add_f32 v[144:145], v[144:145], 1.0 op_sel_hi:[1,0]
	s_nop 0
	v_div_scale_f32 v0, s[28:29], v145, v145, 1.0
	v_rcp_f32_e32 v149, v0
	v_cvt_pk_bf16_f32 v156, v156, v157
	v_fma_f32 v158, -v0, v149, 1.0
	v_fmac_f32_e32 v149, v158, v149
	v_div_scale_f32 v158, vcc, 1.0, v145, 1.0
	v_mul_f32_e32 v159, v158, v149
	v_fma_f32 v160, -v0, v159, v158
	v_fmac_f32_e32 v159, v160, v149
	v_fma_f32 v0, -v0, v159, v158
	v_div_fmas_f32 v0, v0, v149, v159
	v_div_fixup_f32 v145, v0, v145, 1.0
	v_div_scale_f32 v0, s[28:29], v144, v144, 1.0
	v_rcp_f32_e32 v149, v0
	s_nop 0
	v_fma_f32 v158, -v0, v149, 1.0
	v_fmac_f32_e32 v149, v158, v149
	v_div_scale_f32 v158, vcc, 1.0, v144, 1.0
	v_mul_f32_e32 v159, v158, v149
	v_fma_f32 v160, -v0, v159, v158
	v_fmac_f32_e32 v159, v160, v149
	v_fma_f32 v0, -v0, v159, v158
	v_div_fmas_f32 v0, v0, v149, v159
	v_div_fixup_f32 v144, v0, v144, 1.0
	v_lshlrev_b32_e32 v0, 16, v146
	v_mul_f32_e32 v0, 0xbfb8aa3b, v0
	v_exp_f32_e32 v158, v0
; __device__ __forceinline__ unsigned pkh(float lo, float hi) { f32v2_t v; v.x = lo; v.y = hi; return __builtin_bit_cast(unsigned, __builtin_convertvector(v, bf16v2_t)); }
; __device__ __forceinline__ float bf_lo(unsigned w) { return __uint_as_float(w << 16); }
; __device__ __forceinline__ float bf_hi(unsigned w) { return __uint_as_float(w & 0xffff0000u); }
; __device__ __forceinline__ float sigmoidf_(float x) { return 1.0f / (1.0f + __expf(-x)); }
;     template <int MODE> __device__ __forceinline__ void run(const pg8::f32x4 (&acc)[2][2][4][2], const pg8::Unit& u, int wr, int wc, int fr, int fq) const {
;     ...
;                     if constexpr (MODE == 6) { const u32x4 g = gpre[q];
;                         v[0] *= sigmoidf_(bf_lo(g.x)); v[1] *= sigmoidf_(bf_hi(g.x)); v[2] *= sigmoidf_(bf_lo(g.y)); v[3] *= sigmoidf_(bf_hi(g.y));
;                         v[4] *= sigmoidf_(bf_lo(g.z)); v[5] *= sigmoidf_(bf_hi(g.z)); v[6] *= sigmoidf_(bf_lo(g.w)); v[7] *= sigmoidf_(bf_hi(g.w)); }
;                     u32x4 w; w.x = pkh(v[0], v[1]); w.y = pkh(v[2], v[3]); w.z = pkh(v[4], v[5]); w.w = pkh(v[6], v[7]);
;                     *(u32x4*)(ob + (size_t)row * LDC + col) = w; }
	v_and_b32_e32 v0, 0xffff0000, v146
	v_mul_f32_e32 v0, 0xbfb8aa3b, v0
	v_exp_f32_e32 v159, v0
	v_pk_mul_f32 v[144:145], v[78:79], v[144:145]
	v_pk_add_f32 v[158:159], v[158:159], 1.0 op_sel_hi:[1,0]
	s_nop 0
	v_div_scale_f32 v0, s[28:29], v159, v159, 1.0
	v_rcp_f32_e32 v146, v0
	v_cvt_pk_bf16_f32 v157, v144, v145
	v_lshlrev_b64 v[144:145], 12, v[154:155]
	v_lshl_add_u64 v[144:145], s[10:11], 0, v[144:145]
	v_fma_f32 v149, -v0, v146, 1.0
	v_fmac_f32_e32 v146, v149, v146
	v_div_scale_f32 v149, vcc, 1.0, v159, 1.0
	v_mul_f32_e32 v160, v149, v146
	v_fma_f32 v161, -v0, v160, v149
	v_fmac_f32_e32 v160, v161, v146
	v_fma_f32 v0, -v0, v160, v149
	v_div_fmas_f32 v0, v0, v146, v160
	v_div_fixup_f32 v159, v0, v159, 1.0
	v_div_scale_f32 v0, s[28:29], v158, v158, 1.0
	v_rcp_f32_e32 v146, v0
	v_lshl_add_u64 v[144:145], v[144:145], 0, v[2:3]
	v_fma_f32 v149, -v0, v146, 1.0
	v_fmac_f32_e32 v146, v149, v146
	v_div_scale_f32 v149, vcc, 1.0, v158, 1.0
	v_mul_f32_e32 v160, v149, v146
	v_fma_f32 v161, -v0, v160, v149
	v_fmac_f32_e32 v160, v161, v146
	v_fma_f32 v0, -v0, v160, v149
	v_div_fmas_f32 v0, v0, v146, v160
	v_div_fixup_f32 v158, v0, v158, 1.0
	v_lshlrev_b32_e32 v0, 16, v147
	v_mul_f32_e32 v0, 0xbfb8aa3b, v0
	v_exp_f32_e32 v146, v0
	v_and_b32_e32 v0, 0xffff0000, v147
	v_mul_f32_e32 v0, 0xbfb8aa3b, v0
	v_exp_f32_e32 v147, v0
	v_pk_mul_f32 v[158:159], v[80:81], v[158:159]
	v_pk_add_f32 v[146:147], v[146:147], 1.0 op_sel_hi:[1,0]
	s_nop 0
	v_div_scale_f32 v0, s[28:29], v147, v147, 1.0
	v_rcp_f32_e32 v149, v0
	v_cvt_pk_bf16_f32 v158, v158, v159
	v_fma_f32 v160, -v0, v149, 1.0
	v_fmac_f32_e32 v149, v160, v149
	v_div_scale_f32 v160, vcc, 1.0, v147, 1.0
	v_mul_f32_e32 v161, v160, v149
	v_fma_f32 v162, -v0, v161, v160
	v_fmac_f32_e32 v161, v162, v149
	v_fma_f32 v0, -v0, v161, v160
	v_div_fmas_f32 v0, v0, v149, v161
	v_div_fixup_f32 v147, v0, v147, 1.0
	v_div_scale_f32 v0, s[28:29], v146, v146, 1.0
	v_rcp_f32_e32 v149, v0
	s_nop 0
	v_fma_f32 v160, -v0, v149, 1.0
	v_fmac_f32_e32 v149, v160, v149
	v_div_scale_f32 v160, vcc, 1.0, v146, 1.0
	v_mul_f32_e32 v161, v160, v149
	v_fma_f32 v162, -v0, v161, v160
	v_fmac_f32_e32 v161, v162, v149
	v_fma_f32 v0, -v0, v161, v160
	v_div_fmas_f32 v0, v0, v149, v161
	v_div_fixup_f32 v146, v0, v146, 1.0
	v_lshlrev_b32_e32 v0, 16, v140
	v_pk_mul_f32 v[146:147], v[82:83], v[146:147]
	v_mul_f32_e32 v0, 0xbfb8aa3b, v0
	v_cvt_pk_bf16_f32 v159, v146, v147
	v_exp_f32_e32 v146, v0
	v_and_b32_e32 v0, 0xffff0000, v140
	v_mul_f32_e32 v0, 0xbfb8aa3b, v0
	v_exp_f32_e32 v147, v0
	global_store_dwordx4 v[144:145], v[156:159], off sc1
	v_pk_add_f32 v[146:147], v[146:147], 1.0 op_sel_hi:[1,0]
	s_nop 0
	v_div_scale_f32 v0, s[28:29], v147, v147, 1.0
	v_rcp_f32_e32 v140, v0
	s_nop 0
	v_fma_f32 v149, -v0, v140, 1.0
	v_fmac_f32_e32 v140, v149, v140
	v_div_scale_f32 v149, vcc, 1.0, v147, 1.0
	v_mul_f32_e32 v154, v149, v140
	v_fma_f32 v155, -v0, v154, v149
	v_fmac_f32_e32 v154, v155, v140
	v_fma_f32 v0, -v0, v154, v149
	v_div_fmas_f32 v0, v0, v140, v154
	v_div_fixup_f32 v147, v0, v147, 1.0
	v_div_scale_f32 v0, s[28:29], v146, v146, 1.0
	v_rcp_f32_e32 v140, v0
	s_nop 0
	v_fma_f32 v149, -v0, v140, 1.0
	v_fmac_f32_e32 v140, v149, v140
	v_div_scale_f32 v149, vcc, 1.0, v146, 1.0
	v_mul_f32_e32 v154, v149, v140
	v_fma_f32 v155, -v0, v154, v149
	v_fmac_f32_e32 v154, v155, v140
	v_fma_f32 v0, -v0, v154, v149
	v_div_fmas_f32 v0, v0, v140, v154
	v_div_fixup_f32 v146, v0, v146, 1.0
	v_lshlrev_b32_e32 v0, 16, v141
	v_mul_f32_e32 v0, 0xbfb8aa3b, v0
	v_exp_f32_e32 v140, v0
	v_and_b32_e32 v0, 0xffff0000, v141
	v_mul_f32_e32 v0, 0xbfb8aa3b, v0
	v_exp_f32_e32 v141, v0
	v_pk_mul_f32 v[146:147], v[92:93], v[146:147]
	v_pk_add_f32 v[140:141], v[140:141], 1.0 op_sel_hi:[1,0]
	s_nop 0
	v_div_scale_f32 v0, s[28:29], v141, v141, 1.0
	v_rcp_f32_e32 v149, v0
	s_nop 0
	v_fma_f32 v154, -v0, v149, 1.0
	v_fmac_f32_e32 v149, v154, v149
	v_div_scale_f32 v154, vcc, 1.0, v141, 1.0
	v_mul_f32_e32 v155, v154, v149
	v_fma_f32 v156, -v0, v155, v154
	v_fmac_f32_e32 v155, v156, v149
	v_fma_f32 v0, -v0, v155, v154
	v_div_fmas_f32 v0, v0, v149, v155
	v_div_fixup_f32 v141, v0, v141, 1.0
	v_div_scale_f32 v0, s[28:29], v140, v140, 1.0
	v_rcp_f32_e32 v149, v0
	s_nop 0
	v_fma_f32 v154, -v0, v149, 1.0
	v_fmac_f32_e32 v149, v154, v149
	v_div_scale_f32 v154, vcc, 1.0, v140, 1.0
	v_mul_f32_e32 v155, v154, v149
	v_fma_f32 v156, -v0, v155, v154
	v_fmac_f32_e32 v155, v156, v149
	v_fma_f32 v0, -v0, v155, v154
	v_div_fmas_f32 v0, v0, v149, v155
	v_div_fixup_f32 v140, v0, v140, 1.0
	v_lshlrev_b32_e32 v0, 16, v142
	v_mul_f32_e32 v0, 0xbfb8aa3b, v0
	v_pk_mul_f32 v[154:155], v[94:95], v[140:141]
	v_exp_f32_e32 v140, v0
	v_and_b32_e32 v0, 0xffff0000, v142
	v_mul_f32_e32 v0, 0xbfb8aa3b, v0
	v_exp_f32_e32 v141, v0
	s_nop 0
	v_pk_add_f32 v[140:141], v[140:141], 1.0 op_sel_hi:[1,0]
	s_nop 0
	v_div_scale_f32 v0, s[28:29], v141, v141, 1.0
	v_rcp_f32_e32 v142, v0
	s_nop 0
	v_fma_f32 v149, -v0, v142, 1.0
	v_fmac_f32_e32 v142, v149, v142
	v_div_scale_f32 v149, vcc, 1.0, v141, 1.0
	v_mul_f32_e32 v156, v149, v142
	v_fma_f32 v157, -v0, v156, v149
	v_fmac_f32_e32 v156, v157, v142
	v_fma_f32 v0, -v0, v156, v149
	v_div_fmas_f32 v0, v0, v142, v156
	v_div_fixup_f32 v141, v0, v141, 1.0
	v_div_scale_f32 v0, s[28:29], v140, v140, 1.0
	v_rcp_f32_e32 v142, v0
	s_nop 0
	v_fma_f32 v149, -v0, v142, 1.0
	v_fmac_f32_e32 v142, v149, v142
	v_div_scale_f32 v149, vcc, 1.0, v140, 1.0
	v_mul_f32_e32 v156, v149, v142
	v_fma_f32 v157, -v0, v156, v149
	v_fmac_f32_e32 v156, v157, v142
	v_fma_f32 v0, -v0, v156, v149
	v_div_fmas_f32 v0, v0, v142, v156
	v_div_fixup_f32 v140, v0, v140, 1.0
	v_lshlrev_b32_e32 v0, 16, v143
	v_mul_f32_e32 v0, 0xbfb8aa3b, v0
; __device__ __forceinline__ unsigned pkh(float lo, float hi) { f32v2_t v; v.x = lo; v.y = hi; return __builtin_bit_cast(unsigned, __builtin_convertvector(v, bf16v2_t)); }
; __device__ __forceinline__ float bf_lo(unsigned w) { return __uint_as_float(w << 16); }
; __device__ __forceinline__ float bf_hi(unsigned w) { return __uint_as_float(w & 0xffff0000u); }
; __device__ __forceinline__ float sigmoidf_(float x) { return 1.0f / (1.0f + __expf(-x)); }
;     template <int MODE> __device__ __forceinline__ void run(const pg8::f32x4 (&acc)[2][2][4][2], const pg8::Unit& u, int wr, int wc, int fr, int fq) const {
;     ...
;                     if constexpr (MODE == 6) { const u32x4 g = gpre[q];
;                         v[0] *= sigmoidf_(bf_lo(g.x)); v[1] *= sigmoidf_(bf_hi(g.x)); v[2] *= sigmoidf_(bf_lo(g.y)); v[3] *= sigmoidf_(bf_hi(g.y));
;                         v[4] *= sigmoidf_(bf_lo(g.z)); v[5] *= sigmoidf_(bf_hi(g.z)); v[6] *= sigmoidf_(bf_lo(g.w)); v[7] *= sigmoidf_(bf_hi(g.w)); }
;                     u32x4 w; w.x = pkh(v[0], v[1]); w.y = pkh(v[2], v[3]); w.z = pkh(v[4], v[5]); w.w = pkh(v[6], v[7]);
;                     *(u32x4*)(ob + (size_t)row * LDC + col) = w; }
	v_pk_mul_f32 v[156:157], v[96:97], v[140:141]
	v_exp_f32_e32 v140, v0
	v_and_b32_e32 v0, 0xffff0000, v143
	v_mul_f32_e32 v0, 0xbfb8aa3b, v0
	v_exp_f32_e32 v141, v0
	s_nop 0
	v_pk_add_f32 v[140:141], v[140:141], 1.0 op_sel_hi:[1,0]
	s_nop 0
	v_div_scale_f32 v0, s[28:29], v141, v141, 1.0
	v_rcp_f32_e32 v142, v0
	s_nop 0
	v_fma_f32 v143, -v0, v142, 1.0
	v_fmac_f32_e32 v142, v143, v142
	v_div_scale_f32 v143, vcc, 1.0, v141, 1.0
	v_mul_f32_e32 v149, v143, v142
	v_fma_f32 v158, -v0, v149, v143
	v_fmac_f32_e32 v149, v158, v142
	v_fma_f32 v0, -v0, v149, v143
	v_div_fmas_f32 v0, v0, v142, v149
	v_div_fixup_f32 v141, v0, v141, 1.0
	v_div_scale_f32 v0, s[28:29], v140, v140, 1.0
	v_rcp_f32_e32 v142, v0
	s_nop 0
	v_fma_f32 v143, -v0, v142, 1.0
	v_fmac_f32_e32 v142, v143, v142
	v_div_scale_f32 v143, vcc, 1.0, v140, 1.0
	v_mul_f32_e32 v149, v143, v142
	v_fma_f32 v158, -v0, v149, v143
	v_fmac_f32_e32 v149, v158, v142
	v_fma_f32 v0, -v0, v149, v143
	v_div_fmas_f32 v0, v0, v142, v149
	v_div_fixup_f32 v140, v0, v140, 1.0
	v_pk_mul_f32 v[158:159], v[98:99], v[140:141]
	v_lshlrev_b32_e32 v0, 16, v136
	v_cvt_pk_bf16_f32 v140, v146, v147
	v_cvt_pk_bf16_f32 v141, v154, v155
	v_cvt_pk_bf16_f32 v142, v156, v157
	v_cvt_pk_bf16_f32 v143, v158, v159
	v_mul_f32_e32 v0, 0xbfb8aa3b, v0
	global_store_dwordx4 v[144:145], v[140:143], off offset:256 sc1
	v_add_u32_e32 v156, 0x80, v148
	v_ashrrev_i32_e32 v157, 31, v156
	v_exp_f32_e32 v142, v0
	v_and_b32_e32 v0, 0xffff0000, v136
	v_mul_f32_e32 v0, 0xbfb8aa3b, v0
	v_exp_f32_e32 v143, v0
	v_or_b32_e32 v140, 48, v148
	v_add_u32_e32 v154, 0x90, v148
	v_pk_add_f32 v[142:143], v[142:143], 1.0 op_sel_hi:[1,0]
	s_nop 0
	v_div_scale_f32 v0, s[28:29], v143, v143, 1.0
	v_rcp_f32_e32 v136, v0
	s_nop 0
	v_fma_f32 v141, -v0, v136, 1.0
	v_fmac_f32_e32 v136, v141, v136
	v_div_scale_f32 v141, vcc, 1.0, v143, 1.0
	v_mul_f32_e32 v144, v141, v136
	v_fma_f32 v145, -v0, v144, v141
	v_fmac_f32_e32 v144, v145, v136
	v_fma_f32 v0, -v0, v144, v141
	v_div_fmas_f32 v0, v0, v136, v144
	v_div_fixup_f32 v143, v0, v143, 1.0
	v_div_scale_f32 v0, s[28:29], v142, v142, 1.0
	v_rcp_f32_e32 v136, v0
	s_nop 0
	v_fma_f32 v141, -v0, v136, 1.0
	v_fmac_f32_e32 v136, v141, v136
	v_div_scale_f32 v141, vcc, 1.0, v142, 1.0
	v_mul_f32_e32 v144, v141, v136
	v_fma_f32 v145, -v0, v144, v141
	v_fmac_f32_e32 v144, v145, v136
	v_fma_f32 v0, -v0, v144, v141
	v_div_fmas_f32 v0, v0, v136, v144
	v_div_fixup_f32 v142, v0, v142, 1.0
	v_lshlrev_b32_e32 v0, 16, v137
	v_mul_f32_e32 v0, 0xbfb8aa3b, v0
	v_exp_f32_e32 v136, v0
	v_and_b32_e32 v0, 0xffff0000, v137
	v_mul_f32_e32 v0, 0xbfb8aa3b, v0
	v_exp_f32_e32 v137, v0
	v_pk_mul_f32 v[142:143], v[44:45], v[142:143]
	v_pk_add_f32 v[136:137], v[136:137], 1.0 op_sel_hi:[1,0]
	s_nop 0
	v_div_scale_f32 v0, s[28:29], v137, v137, 1.0
	v_rcp_f32_e32 v141, v0
	v_cvt_pk_bf16_f32 v142, v142, v143
	v_fma_f32 v144, -v0, v141, 1.0
	v_fmac_f32_e32 v141, v144, v141
	v_div_scale_f32 v144, vcc, 1.0, v137, 1.0
	v_mul_f32_e32 v145, v144, v141
	v_fma_f32 v146, -v0, v145, v144
	v_fmac_f32_e32 v145, v146, v141
	v_fma_f32 v0, -v0, v145, v144
	v_div_fmas_f32 v0, v0, v141, v145
	v_div_fixup_f32 v137, v0, v137, 1.0
	v_div_scale_f32 v0, s[28:29], v136, v136, 1.0
	v_rcp_f32_e32 v141, v0
	s_nop 0
	v_fma_f32 v144, -v0, v141, 1.0
	v_fmac_f32_e32 v141, v144, v141
	v_div_scale_f32 v144, vcc, 1.0, v136, 1.0
	v_mul_f32_e32 v145, v144, v141
	v_fma_f32 v146, -v0, v145, v144
	v_fmac_f32_e32 v145, v146, v141
	v_fma_f32 v0, -v0, v145, v144
	v_div_fmas_f32 v0, v0, v141, v145
	v_div_fixup_f32 v136, v0, v136, 1.0
	v_lshlrev_b32_e32 v0, 16, v138
	v_mul_f32_e32 v0, 0xbfb8aa3b, v0
	v_exp_f32_e32 v144, v0
	v_and_b32_e32 v0, 0xffff0000, v138
	v_mul_f32_e32 v0, 0xbfb8aa3b, v0
	v_exp_f32_e32 v145, v0
	v_pk_mul_f32 v[136:137], v[46:47], v[136:137]
	v_pk_add_f32 v[144:145], v[144:145], 1.0 op_sel_hi:[1,0]
	s_nop 0
	v_div_scale_f32 v0, s[28:29], v145, v145, 1.0
	v_rcp_f32_e32 v138, v0
	v_cvt_pk_bf16_f32 v143, v136, v137
	v_fma_f32 v141, -v0, v138, 1.0
	v_fmac_f32_e32 v138, v141, v138
	v_div_scale_f32 v141, vcc, 1.0, v145, 1.0
	v_mul_f32_e32 v146, v141, v138
	v_fma_f32 v147, -v0, v146, v141
	v_fmac_f32_e32 v146, v147, v138
	v_fma_f32 v0, -v0, v146, v141
	v_div_fmas_f32 v0, v0, v138, v146
	v_div_fixup_f32 v145, v0, v145, 1.0
	v_div_scale_f32 v0, s[28:29], v144, v144, 1.0
	v_rcp_f32_e32 v138, v0
	s_nop 0
	v_fma_f32 v141, -v0, v138, 1.0
	v_fmac_f32_e32 v138, v141, v138
	v_div_scale_f32 v141, vcc, 1.0, v144, 1.0
	v_mul_f32_e32 v146, v141, v138
	v_fma_f32 v147, -v0, v146, v141
	v_fmac_f32_e32 v146, v147, v138
	v_fma_f32 v0, -v0, v146, v141
	v_div_fmas_f32 v0, v0, v138, v146
	v_div_fixup_f32 v144, v0, v144, 1.0
	v_lshlrev_b32_e32 v0, 16, v139
	v_mul_f32_e32 v0, 0xbfb8aa3b, v0
	v_exp_f32_e32 v138, v0
	v_and_b32_e32 v0, 0xffff0000, v139
	v_mul_f32_e32 v0, 0xbfb8aa3b, v0
	v_exp_f32_e32 v139, v0
	v_pk_mul_f32 v[144:145], v[48:49], v[144:145]
	v_pk_add_f32 v[138:139], v[138:139], 1.0 op_sel_hi:[1,0]
	s_nop 0
	v_div_scale_f32 v0, s[28:29], v139, v139, 1.0
	v_rcp_f32_e32 v141, v0
	v_cvt_pk_bf16_f32 v144, v144, v145
	v_fma_f32 v146, -v0, v141, 1.0
	v_fmac_f32_e32 v141, v146, v141
	v_div_scale_f32 v146, vcc, 1.0, v139, 1.0
	v_mul_f32_e32 v147, v146, v141
	v_fma_f32 v149, -v0, v147, v146
	v_fmac_f32_e32 v147, v149, v141
	v_fma_f32 v0, -v0, v147, v146
	v_div_fmas_f32 v0, v0, v141, v147
	v_div_fixup_f32 v139, v0, v139, 1.0
	v_div_scale_f32 v0, s[28:29], v138, v138, 1.0
	v_rcp_f32_e32 v141, v0
	s_nop 0
	v_fma_f32 v146, -v0, v141, 1.0
	v_fmac_f32_e32 v141, v146, v141
	v_div_scale_f32 v146, vcc, 1.0, v138, 1.0
	v_mul_f32_e32 v147, v146, v141
	v_fma_f32 v149, -v0, v147, v146
	v_fmac_f32_e32 v147, v149, v141
	v_fma_f32 v0, -v0, v147, v146
	v_div_fmas_f32 v0, v0, v141, v147
	v_div_fixup_f32 v138, v0, v138, 1.0
	s_waitcnt vmcnt(0)
; __device__ __forceinline__ unsigned pkh(float lo, float hi) { f32v2_t v; v.x = lo; v.y = hi; return __builtin_bit_cast(unsigned, __builtin_convertvector(v, bf16v2_t)); }
; __device__ __forceinline__ float bf_lo(unsigned w) { return __uint_as_float(w << 16); }
; __device__ __forceinline__ float bf_hi(unsigned w) { return __uint_as_float(w & 0xffff0000u); }
; __device__ __forceinline__ float sigmoidf_(float x) { return 1.0f / (1.0f + __expf(-x)); }
;     template <int MODE> __device__ __forceinline__ void run(const pg8::f32x4 (&acc)[2][2][4][2], const pg8::Unit& u, int wr, int wc, int fr, int fq) const {
;     ...
;                     for (int q = 0; q < 4; ++q) { const int m = 2 * mp + (q >> 1), bj = q & 1; const int row = u.pm * 256 + ai * 128 + wr * 64 + m * 16 + fr, col = u.pn * 256 + bj * 128 + wc * 32 + 8 * fq;
;                         gpre[q] = *(const u32x4*)(proj + (size_t)row * NP + OFF_MG + 2 * DM + col); }
;                 }
; #pragma unroll
;                 for (int q = 0; q < 4; ++q) { const int m = 2 * mp + (q >> 1), bj = q & 1; const int row = u.pm * 256 + ai * 128 + wr * 64 + m * 16 + fr, col = u.pn * 256 + bj * 128 + wc * 32 + 8 * fq;
;                     const pg8::f32x4 t0 = acc[ai][bj][m][0], t1 = acc[ai][bj][m][1];
;                     float v[8] = {t0[0], t0[1], t0[2], t0[3], t1[0], t1[1], t1[2], t1[3]};
;                     if constexpr (MODE == 5) {
; #pragma unroll
;                         for (int e = 0; e < 8; ++e) { const float r = fmaxf(v[e], 0.f); v[e] = r * r; }
;                     }
;                     if constexpr (MODE == 6) { const u32x4 g = gpre[q];
;                         v[0] *= sigmoidf_(bf_lo(g.x)); v[1] *= sigmoidf_(bf_hi(g.x)); v[2] *= sigmoidf_(bf_lo(g.y)); v[3] *= sigmoidf_(bf_hi(g.y));
;                         v[4] *= sigmoidf_(bf_lo(g.z)); v[5] *= sigmoidf_(bf_hi(g.z)); v[6] *= sigmoidf_(bf_lo(g.w)); v[7] *= sigmoidf_(bf_hi(g.w)); }
;                     u32x4 w; w.x = pkh(v[0], v[1]); w.y = pkh(v[2], v[3]); w.z = pkh(v[4], v[5]); w.w = pkh(v[6], v[7]);
;                     *(u32x4*)(ob + (size_t)row * LDC + col) = w; }
	v_lshlrev_b32_e32 v0, 16, v132
	v_pk_mul_f32 v[138:139], v[50:51], v[138:139]
	v_mul_f32_e32 v0, 0xbfb8aa3b, v0
	v_cvt_pk_bf16_f32 v145, v138, v139
	v_exp_f32_e32 v138, v0
	v_and_b32_e32 v0, 0xffff0000, v132
	v_mul_f32_e32 v0, 0xbfb8aa3b, v0
	v_exp_f32_e32 v139, v0
	v_ashrrev_i32_e32 v141, 31, v140
	v_lshlrev_b64 v[136:137], 12, v[140:141]
	v_lshl_add_u64 v[136:137], s[10:11], 0, v[136:137]
	v_pk_add_f32 v[138:139], v[138:139], 1.0 op_sel_hi:[1,0]
	v_lshl_add_u64 v[136:137], v[136:137], 0, v[2:3]
	v_div_scale_f32 v0, s[28:29], v139, v139, 1.0
	v_rcp_f32_e32 v132, v0
	global_store_dwordx4 v[136:137], v[142:145], off sc1
	v_fma_f32 v140, -v0, v132, 1.0
	v_fmac_f32_e32 v132, v140, v132
	v_div_scale_f32 v140, vcc, 1.0, v139, 1.0
	v_mul_f32_e32 v141, v140, v132
	v_fma_f32 v142, -v0, v141, v140
	v_fmac_f32_e32 v141, v142, v132
	v_fma_f32 v0, -v0, v141, v140
	v_div_fmas_f32 v0, v0, v132, v141
	v_div_fixup_f32 v139, v0, v139, 1.0
	v_div_scale_f32 v0, s[28:29], v138, v138, 1.0
	v_rcp_f32_e32 v132, v0
	s_nop 0
	v_fma_f32 v140, -v0, v132, 1.0
	v_fmac_f32_e32 v132, v140, v132
	v_div_scale_f32 v140, vcc, 1.0, v138, 1.0
	v_mul_f32_e32 v141, v140, v132
	v_fma_f32 v142, -v0, v141, v140
	v_fmac_f32_e32 v141, v142, v132
	v_fma_f32 v0, -v0, v141, v140
	v_div_fmas_f32 v0, v0, v132, v141
	v_div_fixup_f32 v138, v0, v138, 1.0
	v_lshlrev_b32_e32 v0, 16, v133
	v_mul_f32_e32 v0, 0xbfb8aa3b, v0
	v_exp_f32_e32 v132, v0
	v_and_b32_e32 v0, 0xffff0000, v133
	v_mul_f32_e32 v0, 0xbfb8aa3b, v0
	v_exp_f32_e32 v133, v0
	v_pk_mul_f32 v[138:139], v[68:69], v[138:139]
	v_pk_add_f32 v[132:133], v[132:133], 1.0 op_sel_hi:[1,0]
	s_nop 0
	v_div_scale_f32 v0, s[28:29], v133, v133, 1.0
	v_rcp_f32_e32 v140, v0
	s_nop 0
	v_fma_f32 v141, -v0, v140, 1.0
	v_fmac_f32_e32 v140, v141, v140
	v_div_scale_f32 v141, vcc, 1.0, v133, 1.0
	v_mul_f32_e32 v142, v141, v140
	v_fma_f32 v143, -v0, v142, v141
	v_fmac_f32_e32 v142, v143, v140
	v_fma_f32 v0, -v0, v142, v141
	v_div_fmas_f32 v0, v0, v140, v142
	v_div_fixup_f32 v133, v0, v133, 1.0
	v_div_scale_f32 v0, s[28:29], v132, v132, 1.0
	v_rcp_f32_e32 v140, v0
	s_nop 0
	v_fma_f32 v141, -v0, v140, 1.0
	v_fmac_f32_e32 v140, v141, v140
	v_div_scale_f32 v141, vcc, 1.0, v132, 1.0
	v_mul_f32_e32 v142, v141, v140
	v_fma_f32 v143, -v0, v142, v141
	v_fmac_f32_e32 v142, v143, v140
	v_fma_f32 v0, -v0, v142, v141
	v_div_fmas_f32 v0, v0, v140, v142
	v_div_fixup_f32 v132, v0, v132, 1.0
	v_lshlrev_b32_e32 v0, 16, v134
	v_mul_f32_e32 v0, 0xbfb8aa3b, v0
	v_pk_mul_f32 v[140:141], v[70:71], v[132:133]
	v_exp_f32_e32 v132, v0
	v_and_b32_e32 v0, 0xffff0000, v134
	v_mul_f32_e32 v0, 0xbfb8aa3b, v0
	v_exp_f32_e32 v133, v0
	s_nop 0
	v_pk_add_f32 v[132:133], v[132:133], 1.0 op_sel_hi:[1,0]
	s_nop 0
	v_div_scale_f32 v0, s[28:29], v133, v133, 1.0
	v_rcp_f32_e32 v134, v0
	s_nop 0
	v_fma_f32 v142, -v0, v134, 1.0
	v_fmac_f32_e32 v134, v142, v134
	v_div_scale_f32 v142, vcc, 1.0, v133, 1.0
	v_mul_f32_e32 v143, v142, v134
	v_fma_f32 v144, -v0, v143, v142
	v_fmac_f32_e32 v143, v144, v134
	v_fma_f32 v0, -v0, v143, v142
	v_div_fmas_f32 v0, v0, v134, v143
	v_div_fixup_f32 v133, v0, v133, 1.0
	v_div_scale_f32 v0, s[28:29], v132, v132, 1.0
	v_rcp_f32_e32 v134, v0
	s_nop 0
	v_fma_f32 v142, -v0, v134, 1.0
	v_fmac_f32_e32 v134, v142, v134
	v_div_scale_f32 v142, vcc, 1.0, v132, 1.0
	v_mul_f32_e32 v143, v142, v134
	v_fma_f32 v144, -v0, v143, v142
	v_fmac_f32_e32 v143, v144, v134
	v_fma_f32 v0, -v0, v143, v142
	v_div_fmas_f32 v0, v0, v134, v143
	v_div_fixup_f32 v132, v0, v132, 1.0
	v_lshlrev_b32_e32 v0, 16, v135
	v_mul_f32_e32 v0, 0xbfb8aa3b, v0
	v_pk_mul_f32 v[142:143], v[72:73], v[132:133]
	v_exp_f32_e32 v132, v0
	v_and_b32_e32 v0, 0xffff0000, v135
	v_mul_f32_e32 v0, 0xbfb8aa3b, v0
	v_exp_f32_e32 v133, v0
	s_nop 0
	v_pk_add_f32 v[132:133], v[132:133], 1.0 op_sel_hi:[1,0]
	s_nop 0
	v_div_scale_f32 v0, s[28:29], v133, v133, 1.0
	v_rcp_f32_e32 v134, v0
	s_nop 0
	v_fma_f32 v135, -v0, v134, 1.0
	v_fmac_f32_e32 v134, v135, v134
	v_div_scale_f32 v135, vcc, 1.0, v133, 1.0
	v_mul_f32_e32 v144, v135, v134
	v_fma_f32 v145, -v0, v144, v135
	v_fmac_f32_e32 v144, v145, v134
	v_fma_f32 v0, -v0, v144, v135
	v_div_fmas_f32 v0, v0, v134, v144
	v_div_fixup_f32 v133, v0, v133, 1.0
	v_div_scale_f32 v0, s[28:29], v132, v132, 1.0
	v_rcp_f32_e32 v134, v0
	s_nop 0
	v_fma_f32 v135, -v0, v134, 1.0
	v_fmac_f32_e32 v134, v135, v134
	v_div_scale_f32 v135, vcc, 1.0, v132, 1.0
	v_mul_f32_e32 v144, v135, v134
	v_fma_f32 v145, -v0, v144, v135
	v_fmac_f32_e32 v144, v145, v134
	v_fma_f32 v0, -v0, v144, v135
	v_div_fmas_f32 v0, v0, v134, v144
	v_div_fixup_f32 v132, v0, v132, 1.0
	v_pk_mul_f32 v[144:145], v[74:75], v[132:133]
	v_cvt_pk_bf16_f32 v132, v138, v139
	v_cvt_pk_bf16_f32 v133, v140, v141
	v_cvt_pk_bf16_f32 v134, v142, v143
	v_cvt_pk_bf16_f32 v135, v144, v145
	global_store_dwordx4 v[136:137], v[132:135], off offset:256 sc1
	s_nop 1
	v_mad_i64_i32 v[132:133], s[28:29], v156, s76, v[150:151]
	v_lshl_add_u64 v[132:133], v[132:133], 0, s[30:31]
	v_lshl_add_u64 v[134:135], v[132:133], 0, v[2:3]
	global_load_dwordx4 v[144:147], v[134:135], off
	v_lshl_add_u64 v[132:133], v[132:133], 0, v[152:153]
	global_load_dwordx4 v[140:143], v[132:133], off
	v_mad_i64_i32 v[132:133], s[28:29], v154, s76, v[150:151]
	v_lshl_add_u64 v[132:133], v[132:133], 0, s[30:31]
	v_lshl_add_u64 v[134:135], v[132:133], 0, v[2:3]
	global_load_dwordx4 v[136:139], v[134:135], off
	v_lshl_add_u64 v[132:133], v[132:133], 0, v[152:153]
	global_load_dwordx4 v[132:135], v[132:133], off
	s_waitcnt vmcnt(0)
; __device__ __forceinline__ unsigned pkh(float lo, float hi) { f32v2_t v; v.x = lo; v.y = hi; return __builtin_bit_cast(unsigned, __builtin_convertvector(v, bf16v2_t)); }
; __device__ __forceinline__ float bf_lo(unsigned w) { return __uint_as_float(w << 16); }
; __device__ __forceinline__ float bf_hi(unsigned w) { return __uint_as_float(w & 0xffff0000u); }
; __device__ __forceinline__ float sigmoidf_(float x) { return 1.0f / (1.0f + __expf(-x)); }
;     template <int MODE> __device__ __forceinline__ void run(const pg8::f32x4 (&acc)[2][2][4][2], const pg8::Unit& u, int wr, int wc, int fr, int fq) const {
;     ...
;                 if constexpr (MODE == 6) {
; #pragma unroll
;                     for (int q = 0; q < 4; ++q) { const int m = 2 * mp + (q >> 1), bj = q & 1; const int row = u.pm * 256 + ai * 128 + wr * 64 + m * 16 + fr, col = u.pn * 256 + bj * 128 + wc * 32 + 8 * fq;
;                         gpre[q] = *(const u32x4*)(proj + (size_t)row * NP + OFF_MG + 2 * DM + col); }
;                 }
; #pragma unroll
;                 for (int q = 0; q < 4; ++q) { const int m = 2 * mp + (q >> 1), bj = q & 1; const int row = u.pm * 256 + ai * 128 + wr * 64 + m * 16 + fr, col = u.pn * 256 + bj * 128 + wc * 32 + 8 * fq;
;                     const pg8::f32x4 t0 = acc[ai][bj][m][0], t1 = acc[ai][bj][m][1];
;                     float v[8] = {t0[0], t0[1], t0[2], t0[3], t1[0], t1[1], t1[2], t1[3]};
;                     if constexpr (MODE == 5) {
; #pragma unroll
;                         for (int e = 0; e < 8; ++e) { const float r = fmaxf(v[e], 0.f); v[e] = r * r; }
;                     }
;                     if constexpr (MODE == 6) { const u32x4 g = gpre[q];
;                         v[0] *= sigmoidf_(bf_lo(g.x)); v[1] *= sigmoidf_(bf_hi(g.x)); v[2] *= sigmoidf_(bf_lo(g.y)); v[3] *= sigmoidf_(bf_hi(g.y));
;                         v[4] *= sigmoidf_(bf_lo(g.z)); v[5] *= sigmoidf_(bf_hi(g.z)); v[6] *= sigmoidf_(bf_lo(g.w)); v[7] *= sigmoidf_(bf_hi(g.w)); }
;                     u32x4 w; w.x = pkh(v[0], v[1]); w.y = pkh(v[2], v[3]); w.z = pkh(v[4], v[5]); w.w = pkh(v[6], v[7]);
;                     *(u32x4*)(ob + (size_t)row * LDC + col) = w; }
	v_lshlrev_b32_e32 v0, 16, v144
	v_mul_f32_e32 v0, 0xbfb8aa3b, v0
	v_exp_f32_e32 v158, v0
	v_and_b32_e32 v0, 0xffff0000, v144
	v_mul_f32_e32 v0, 0xbfb8aa3b, v0
	v_exp_f32_e32 v159, v0
	s_nop 0
	v_pk_add_f32 v[158:159], v[158:159], 1.0 op_sel_hi:[1,0]
	s_nop 0
	v_div_scale_f32 v0, s[28:29], v159, v159, 1.0
	v_rcp_f32_e32 v144, v0
	s_nop 0
	v_fma_f32 v149, -v0, v144, 1.0
	v_fmac_f32_e32 v144, v149, v144
	v_div_scale_f32 v149, vcc, 1.0, v159, 1.0
	v_mul_f32_e32 v155, v149, v144
	v_fma_f32 v160, -v0, v155, v149
	v_fmac_f32_e32 v155, v160, v144
	v_fma_f32 v0, -v0, v155, v149
	v_div_fmas_f32 v0, v0, v144, v155
	v_div_fixup_f32 v159, v0, v159, 1.0
	v_div_scale_f32 v0, s[28:29], v158, v158, 1.0
	v_rcp_f32_e32 v144, v0
	s_nop 0
	v_fma_f32 v149, -v0, v144, 1.0
	v_fmac_f32_e32 v144, v149, v144
	v_div_scale_f32 v149, vcc, 1.0, v158, 1.0
	v_mul_f32_e32 v155, v149, v144
	v_fma_f32 v160, -v0, v155, v149
	v_fmac_f32_e32 v155, v160, v144
	v_fma_f32 v0, -v0, v155, v149
	v_div_fmas_f32 v0, v0, v144, v155
	v_div_fixup_f32 v158, v0, v158, 1.0
	v_lshlrev_b32_e32 v0, 16, v145
	v_mul_f32_e32 v0, 0xbfb8aa3b, v0
	v_exp_f32_e32 v144, v0
	v_and_b32_e32 v0, 0xffff0000, v145
	v_mul_f32_e32 v0, 0xbfb8aa3b, v0
	v_exp_f32_e32 v145, v0
	v_pk_mul_f32 v[158:159], v[60:61], v[158:159]
	v_pk_add_f32 v[144:145], v[144:145], 1.0 op_sel_hi:[1,0]
	s_nop 0
	v_div_scale_f32 v0, s[28:29], v145, v145, 1.0
	v_rcp_f32_e32 v149, v0
	v_cvt_pk_bf16_f32 v158, v158, v159
	v_fma_f32 v155, -v0, v149, 1.0
	v_fmac_f32_e32 v149, v155, v149
	v_div_scale_f32 v155, vcc, 1.0, v145, 1.0
	v_mul_f32_e32 v160, v155, v149
	v_fma_f32 v161, -v0, v160, v155
	v_fmac_f32_e32 v160, v161, v149
	v_fma_f32 v0, -v0, v160, v155
	v_div_fmas_f32 v0, v0, v149, v160
	v_div_fixup_f32 v145, v0, v145, 1.0
	v_div_scale_f32 v0, s[28:29], v144, v144, 1.0
	v_rcp_f32_e32 v149, v0
	s_nop 0
	v_fma_f32 v155, -v0, v149, 1.0
	v_fmac_f32_e32 v149, v155, v149
	v_div_scale_f32 v155, vcc, 1.0, v144, 1.0
	v_mul_f32_e32 v160, v155, v149
	v_fma_f32 v161, -v0, v160, v155
	v_fmac_f32_e32 v160, v161, v149
	v_fma_f32 v0, -v0, v160, v155
	v_div_fmas_f32 v0, v0, v149, v160
	v_div_fixup_f32 v144, v0, v144, 1.0
	v_lshlrev_b32_e32 v0, 16, v146
	v_mul_f32_e32 v0, 0xbfb8aa3b, v0
	v_exp_f32_e32 v160, v0
	v_and_b32_e32 v0, 0xffff0000, v146
	v_mul_f32_e32 v0, 0xbfb8aa3b, v0
	v_exp_f32_e32 v161, v0
	v_pk_mul_f32 v[144:145], v[62:63], v[144:145]
	v_pk_add_f32 v[160:161], v[160:161], 1.0 op_sel_hi:[1,0]
	s_nop 0
	v_div_scale_f32 v0, s[28:29], v161, v161, 1.0
	v_rcp_f32_e32 v146, v0
	v_cvt_pk_bf16_f32 v159, v144, v145
	v_lshlrev_b64 v[144:145], 12, v[156:157]
	v_lshl_add_u64 v[144:145], s[10:11], 0, v[144:145]
	v_fma_f32 v149, -v0, v146, 1.0
	v_fmac_f32_e32 v146, v149, v146
	v_div_scale_f32 v149, vcc, 1.0, v161, 1.0
	v_mul_f32_e32 v155, v149, v146
	v_fma_f32 v162, -v0, v155, v149
	v_fmac_f32_e32 v155, v162, v146
	v_fma_f32 v0, -v0, v155, v149
	v_div_fmas_f32 v0, v0, v146, v155
	v_div_fixup_f32 v161, v0, v161, 1.0
	v_div_scale_f32 v0, s[28:29], v160, v160, 1.0
	v_rcp_f32_e32 v146, v0
	v_lshl_add_u64 v[144:145], v[144:145], 0, v[2:3]
	v_fma_f32 v149, -v0, v146, 1.0
	v_fmac_f32_e32 v146, v149, v146
	v_div_scale_f32 v149, vcc, 1.0, v160, 1.0
	v_mul_f32_e32 v155, v149, v146
	v_fma_f32 v162, -v0, v155, v149
	v_fmac_f32_e32 v155, v162, v146
	v_fma_f32 v0, -v0, v155, v149
	v_div_fmas_f32 v0, v0, v146, v155
	v_div_fixup_f32 v160, v0, v160, 1.0
	v_lshlrev_b32_e32 v0, 16, v147
	v_mul_f32_e32 v0, 0xbfb8aa3b, v0
	v_exp_f32_e32 v146, v0
	v_and_b32_e32 v0, 0xffff0000, v147
	v_mul_f32_e32 v0, 0xbfb8aa3b, v0
	v_exp_f32_e32 v147, v0
	v_pk_mul_f32 v[160:161], v[64:65], v[160:161]
	v_pk_add_f32 v[146:147], v[146:147], 1.0 op_sel_hi:[1,0]
	s_nop 0
	v_div_scale_f32 v0, s[28:29], v147, v147, 1.0
	v_rcp_f32_e32 v149, v0
	v_cvt_pk_bf16_f32 v160, v160, v161
	v_fma_f32 v155, -v0, v149, 1.0
	v_fmac_f32_e32 v149, v155, v149
	v_div_scale_f32 v155, vcc, 1.0, v147, 1.0
	v_mul_f32_e32 v162, v155, v149
	v_fma_f32 v163, -v0, v162, v155
	v_fmac_f32_e32 v162, v163, v149
	v_fma_f32 v0, -v0, v162, v155
	v_div_fmas_f32 v0, v0, v149, v162
	v_div_fixup_f32 v147, v0, v147, 1.0
	v_div_scale_f32 v0, s[28:29], v146, v146, 1.0
	v_rcp_f32_e32 v149, v0
	s_nop 0
	v_fma_f32 v155, -v0, v149, 1.0
	v_fmac_f32_e32 v149, v155, v149
	v_div_scale_f32 v155, vcc, 1.0, v146, 1.0
	v_mul_f32_e32 v162, v155, v149
	v_fma_f32 v163, -v0, v162, v155
	v_fmac_f32_e32 v162, v163, v149
	v_fma_f32 v0, -v0, v162, v155
	v_div_fmas_f32 v0, v0, v149, v162
	v_div_fixup_f32 v146, v0, v146, 1.0
	v_lshlrev_b32_e32 v0, 16, v140
	v_pk_mul_f32 v[146:147], v[66:67], v[146:147]
	v_mul_f32_e32 v0, 0xbfb8aa3b, v0
	v_cvt_pk_bf16_f32 v161, v146, v147
	v_exp_f32_e32 v146, v0
	v_and_b32_e32 v0, 0xffff0000, v140
	v_mul_f32_e32 v0, 0xbfb8aa3b, v0
	v_exp_f32_e32 v147, v0
	global_store_dwordx4 v[144:145], v[158:161], off sc1
	v_pk_add_f32 v[146:147], v[146:147], 1.0 op_sel_hi:[1,0]
	s_nop 0
	v_div_scale_f32 v0, s[28:29], v147, v147, 1.0
	v_rcp_f32_e32 v140, v0
	s_nop 0
	v_fma_f32 v149, -v0, v140, 1.0
	v_fmac_f32_e32 v140, v149, v140
	v_div_scale_f32 v149, vcc, 1.0, v147, 1.0
	v_mul_f32_e32 v155, v149, v140
	v_fma_f32 v156, -v0, v155, v149
	v_fmac_f32_e32 v155, v156, v140
	v_fma_f32 v0, -v0, v155, v149
	v_div_fmas_f32 v0, v0, v140, v155
	v_div_fixup_f32 v147, v0, v147, 1.0
	v_div_scale_f32 v0, s[28:29], v146, v146, 1.0
	v_rcp_f32_e32 v140, v0
	s_nop 0
	v_fma_f32 v149, -v0, v140, 1.0
	v_fmac_f32_e32 v140, v149, v140
	v_div_scale_f32 v149, vcc, 1.0, v146, 1.0
	v_mul_f32_e32 v155, v149, v140
	v_fma_f32 v156, -v0, v155, v149
	v_fmac_f32_e32 v155, v156, v140
	v_fma_f32 v0, -v0, v155, v149
	v_div_fmas_f32 v0, v0, v140, v155
	v_div_fixup_f32 v146, v0, v146, 1.0
; __device__ __forceinline__ unsigned pkh(float lo, float hi) { f32v2_t v; v.x = lo; v.y = hi; return __builtin_bit_cast(unsigned, __builtin_convertvector(v, bf16v2_t)); }
; __device__ __forceinline__ float bf_lo(unsigned w) { return __uint_as_float(w << 16); }
; __device__ __forceinline__ float bf_hi(unsigned w) { return __uint_as_float(w & 0xffff0000u); }
; __device__ __forceinline__ float sigmoidf_(float x) { return 1.0f / (1.0f + __expf(-x)); }
;     template <int MODE> __device__ __forceinline__ void run(const pg8::f32x4 (&acc)[2][2][4][2], const pg8::Unit& u, int wr, int wc, int fr, int fq) const {
;     ...
;                 if constexpr (MODE == 6) {
; #pragma unroll
;                     for (int q = 0; q < 4; ++q) { const int m = 2 * mp + (q >> 1), bj = q & 1; const int row = u.pm * 256 + ai * 128 + wr * 64 + m * 16 + fr, col = u.pn * 256 + bj * 128 + wc * 32 + 8 * fq;
;                         gpre[q] = *(const u32x4*)(proj + (size_t)row * NP + OFF_MG + 2 * DM + col); }
;                 }
; #pragma unroll
;                 for (int q = 0; q < 4; ++q) { const int m = 2 * mp + (q >> 1), bj = q & 1; const int row = u.pm * 256 + ai * 128 + wr * 64 + m * 16 + fr, col = u.pn * 256 + bj * 128 + wc * 32 + 8 * fq;
;                     const pg8::f32x4 t0 = acc[ai][bj][m][0], t1 = acc[ai][bj][m][1];
;                     float v[8] = {t0[0], t0[1], t0[2], t0[3], t1[0], t1[1], t1[2], t1[3]};
;                     if constexpr (MODE == 5) {
; #pragma unroll
;                         for (int e = 0; e < 8; ++e) { const float r = fmaxf(v[e], 0.f); v[e] = r * r; }
;                     }
;                     if constexpr (MODE == 6) { const u32x4 g = gpre[q];
;                         v[0] *= sigmoidf_(bf_lo(g.x)); v[1] *= sigmoidf_(bf_hi(g.x)); v[2] *= sigmoidf_(bf_lo(g.y)); v[3] *= sigmoidf_(bf_hi(g.y));
;                         v[4] *= sigmoidf_(bf_lo(g.z)); v[5] *= sigmoidf_(bf_hi(g.z)); v[6] *= sigmoidf_(bf_lo(g.w)); v[7] *= sigmoidf_(bf_hi(g.w)); }
;                     u32x4 w; w.x = pkh(v[0], v[1]); w.y = pkh(v[2], v[3]); w.z = pkh(v[4], v[5]); w.w = pkh(v[6], v[7]);
;                     *(u32x4*)(ob + (size_t)row * LDC + col) = w; }
	v_lshlrev_b32_e32 v0, 16, v141
	v_mul_f32_e32 v0, 0xbfb8aa3b, v0
	v_exp_f32_e32 v140, v0
	v_and_b32_e32 v0, 0xffff0000, v141
	v_mul_f32_e32 v0, 0xbfb8aa3b, v0
	v_exp_f32_e32 v141, v0
	v_pk_mul_f32 v[146:147], v[84:85], v[146:147]
	v_pk_add_f32 v[140:141], v[140:141], 1.0 op_sel_hi:[1,0]
	s_nop 0
	v_div_scale_f32 v0, s[28:29], v141, v141, 1.0
	v_rcp_f32_e32 v149, v0
	s_nop 0
	v_fma_f32 v155, -v0, v149, 1.0
	v_fmac_f32_e32 v149, v155, v149
	v_div_scale_f32 v155, vcc, 1.0, v141, 1.0
	v_mul_f32_e32 v156, v155, v149
	v_fma_f32 v157, -v0, v156, v155
	v_fmac_f32_e32 v156, v157, v149
	v_fma_f32 v0, -v0, v156, v155
	v_div_fmas_f32 v0, v0, v149, v156
	v_div_fixup_f32 v141, v0, v141, 1.0
	v_div_scale_f32 v0, s[28:29], v140, v140, 1.0
	v_rcp_f32_e32 v149, v0
	s_nop 0
	v_fma_f32 v155, -v0, v149, 1.0
	v_fmac_f32_e32 v149, v155, v149
	v_div_scale_f32 v155, vcc, 1.0, v140, 1.0
	v_mul_f32_e32 v156, v155, v149
	v_fma_f32 v157, -v0, v156, v155
	v_fmac_f32_e32 v156, v157, v149
	v_fma_f32 v0, -v0, v156, v155
	v_div_fmas_f32 v0, v0, v149, v156
	v_div_fixup_f32 v140, v0, v140, 1.0
	v_lshlrev_b32_e32 v0, 16, v142
	v_mul_f32_e32 v0, 0xbfb8aa3b, v0
	v_pk_mul_f32 v[156:157], v[86:87], v[140:141]
	v_exp_f32_e32 v140, v0
	v_and_b32_e32 v0, 0xffff0000, v142
	v_mul_f32_e32 v0, 0xbfb8aa3b, v0
	v_exp_f32_e32 v141, v0
	s_nop 0
	v_pk_add_f32 v[140:141], v[140:141], 1.0 op_sel_hi:[1,0]
	s_nop 0
	v_div_scale_f32 v0, s[28:29], v141, v141, 1.0
	v_rcp_f32_e32 v142, v0
	s_nop 0
	v_fma_f32 v149, -v0, v142, 1.0
	v_fmac_f32_e32 v142, v149, v142
	v_div_scale_f32 v149, vcc, 1.0, v141, 1.0
	v_mul_f32_e32 v155, v149, v142
	v_fma_f32 v158, -v0, v155, v149
	v_fmac_f32_e32 v155, v158, v142
	v_fma_f32 v0, -v0, v155, v149
	v_div_fmas_f32 v0, v0, v142, v155
	v_div_fixup_f32 v141, v0, v141, 1.0
	v_div_scale_f32 v0, s[28:29], v140, v140, 1.0
	v_rcp_f32_e32 v142, v0
	s_nop 0
	v_fma_f32 v149, -v0, v142, 1.0
	v_fmac_f32_e32 v142, v149, v142
	v_div_scale_f32 v149, vcc, 1.0, v140, 1.0
	v_mul_f32_e32 v155, v149, v142
	v_fma_f32 v158, -v0, v155, v149
	v_fmac_f32_e32 v155, v158, v142
	v_fma_f32 v0, -v0, v155, v149
	v_div_fmas_f32 v0, v0, v142, v155
	v_div_fixup_f32 v140, v0, v140, 1.0
	v_lshlrev_b32_e32 v0, 16, v143
	v_mul_f32_e32 v0, 0xbfb8aa3b, v0
	v_pk_mul_f32 v[158:159], v[88:89], v[140:141]
	v_exp_f32_e32 v140, v0
	v_and_b32_e32 v0, 0xffff0000, v143
	v_mul_f32_e32 v0, 0xbfb8aa3b, v0
	v_exp_f32_e32 v141, v0
	s_nop 0
	v_pk_add_f32 v[140:141], v[140:141], 1.0 op_sel_hi:[1,0]
	s_nop 0
	v_div_scale_f32 v0, s[28:29], v141, v141, 1.0
	v_rcp_f32_e32 v142, v0
	s_nop 0
	v_fma_f32 v143, -v0, v142, 1.0
	v_fmac_f32_e32 v142, v143, v142
	v_div_scale_f32 v143, vcc, 1.0, v141, 1.0
	v_mul_f32_e32 v149, v143, v142
	v_fma_f32 v155, -v0, v149, v143
	v_fmac_f32_e32 v149, v155, v142
	v_fma_f32 v0, -v0, v149, v143
	v_div_fmas_f32 v0, v0, v142, v149
	v_div_fixup_f32 v141, v0, v141, 1.0
	v_div_scale_f32 v0, s[28:29], v140, v140, 1.0
	v_rcp_f32_e32 v142, v0
	s_nop 0
	v_fma_f32 v143, -v0, v142, 1.0
	v_fmac_f32_e32 v142, v143, v142
	v_div_scale_f32 v143, vcc, 1.0, v140, 1.0
	v_mul_f32_e32 v149, v143, v142
	v_fma_f32 v155, -v0, v149, v143
	v_fmac_f32_e32 v149, v155, v142
	v_fma_f32 v0, -v0, v149, v143
	v_div_fmas_f32 v0, v0, v142, v149
	v_div_fixup_f32 v140, v0, v140, 1.0
	v_pk_mul_f32 v[160:161], v[90:91], v[140:141]
	v_lshlrev_b32_e32 v0, 16, v136
	v_cvt_pk_bf16_f32 v140, v146, v147
	v_cvt_pk_bf16_f32 v141, v156, v157
	v_cvt_pk_bf16_f32 v142, v158, v159
	v_cvt_pk_bf16_f32 v143, v160, v161
	v_mul_f32_e32 v0, 0xbfb8aa3b, v0
	global_store_dwordx4 v[144:145], v[140:143], off offset:256 sc1
	v_ashrrev_i32_e32 v155, 31, v154
	s_nop 0
	v_exp_f32_e32 v140, v0
	v_and_b32_e32 v0, 0xffff0000, v136
	v_mul_f32_e32 v0, 0xbfb8aa3b, v0
	v_exp_f32_e32 v141, v0
	s_nop 0
	v_pk_add_f32 v[140:141], v[140:141], 1.0 op_sel_hi:[1,0]
	s_nop 0
	v_div_scale_f32 v0, s[28:29], v141, v141, 1.0
	v_rcp_f32_e32 v136, v0
	s_nop 0
	v_fma_f32 v142, -v0, v136, 1.0
	v_fmac_f32_e32 v136, v142, v136
	v_div_scale_f32 v142, vcc, 1.0, v141, 1.0
	v_mul_f32_e32 v143, v142, v136
	v_fma_f32 v144, -v0, v143, v142
	v_fmac_f32_e32 v143, v144, v136
	v_fma_f32 v0, -v0, v143, v142
	v_div_fmas_f32 v0, v0, v136, v143
	v_div_fixup_f32 v141, v0, v141, 1.0
	v_div_scale_f32 v0, s[28:29], v140, v140, 1.0
	v_rcp_f32_e32 v136, v0
	s_nop 0
	v_fma_f32 v142, -v0, v136, 1.0
	v_fmac_f32_e32 v136, v142, v136
	v_div_scale_f32 v142, vcc, 1.0, v140, 1.0
	v_mul_f32_e32 v143, v142, v136
	v_fma_f32 v144, -v0, v143, v142
	v_fmac_f32_e32 v143, v144, v136
	v_fma_f32 v0, -v0, v143, v142
	v_div_fmas_f32 v0, v0, v136, v143
	v_div_fixup_f32 v140, v0, v140, 1.0
	v_lshlrev_b32_e32 v0, 16, v137
	v_mul_f32_e32 v0, 0xbfb8aa3b, v0
	v_exp_f32_e32 v136, v0
	v_and_b32_e32 v0, 0xffff0000, v137
	v_mul_f32_e32 v0, 0xbfb8aa3b, v0
	v_exp_f32_e32 v137, v0
	v_pk_mul_f32 v[140:141], v[36:37], v[140:141]
	v_pk_add_f32 v[136:137], v[136:137], 1.0 op_sel_hi:[1,0]
	s_nop 0
	v_div_scale_f32 v0, s[28:29], v137, v137, 1.0
	v_rcp_f32_e32 v142, v0
	s_nop 0
	v_fma_f32 v143, -v0, v142, 1.0
	v_fmac_f32_e32 v142, v143, v142
	v_div_scale_f32 v143, vcc, 1.0, v137, 1.0
	v_mul_f32_e32 v144, v143, v142
	v_fma_f32 v145, -v0, v144, v143
	v_fmac_f32_e32 v144, v145, v142
	v_fma_f32 v0, -v0, v144, v143
	v_div_fmas_f32 v0, v0, v142, v144
	v_div_fixup_f32 v137, v0, v137, 1.0
	v_div_scale_f32 v0, s[28:29], v136, v136, 1.0
	v_rcp_f32_e32 v142, v0
	s_nop 0
	v_fma_f32 v143, -v0, v142, 1.0
	v_fmac_f32_e32 v142, v143, v142
	v_div_scale_f32 v143, vcc, 1.0, v136, 1.0
	v_mul_f32_e32 v144, v143, v142
	v_fma_f32 v145, -v0, v144, v143
	v_fmac_f32_e32 v144, v145, v142
	v_fma_f32 v0, -v0, v144, v143
	v_div_fmas_f32 v0, v0, v142, v144
; __device__ __forceinline__ unsigned pkh(float lo, float hi) { f32v2_t v; v.x = lo; v.y = hi; return __builtin_bit_cast(unsigned, __builtin_convertvector(v, bf16v2_t)); }
; __device__ __forceinline__ float bf_lo(unsigned w) { return __uint_as_float(w << 16); }
; __device__ __forceinline__ float bf_hi(unsigned w) { return __uint_as_float(w & 0xffff0000u); }
; __device__ __forceinline__ float sigmoidf_(float x) { return 1.0f / (1.0f + __expf(-x)); }
;     template <int MODE> __device__ __forceinline__ void run(const pg8::f32x4 (&acc)[2][2][4][2], const pg8::Unit& u, int wr, int wc, int fr, int fq) const {
;     ...
;                 if constexpr (MODE == 6) {
; #pragma unroll
;                     for (int q = 0; q < 4; ++q) { const int m = 2 * mp + (q >> 1), bj = q & 1; const int row = u.pm * 256 + ai * 128 + wr * 64 + m * 16 + fr, col = u.pn * 256 + bj * 128 + wc * 32 + 8 * fq;
;                         gpre[q] = *(const u32x4*)(proj + (size_t)row * NP + OFF_MG + 2 * DM + col); }
;                 }
; #pragma unroll
;                 for (int q = 0; q < 4; ++q) { const int m = 2 * mp + (q >> 1), bj = q & 1; const int row = u.pm * 256 + ai * 128 + wr * 64 + m * 16 + fr, col = u.pn * 256 + bj * 128 + wc * 32 + 8 * fq;
;                     const pg8::f32x4 t0 = acc[ai][bj][m][0], t1 = acc[ai][bj][m][1];
;                     float v[8] = {t0[0], t0[1], t0[2], t0[3], t1[0], t1[1], t1[2], t1[3]};
;                     if constexpr (MODE == 5) {
; #pragma unroll
;                         for (int e = 0; e < 8; ++e) { const float r = fmaxf(v[e], 0.f); v[e] = r * r; }
;                     }
;                     if constexpr (MODE == 6) { const u32x4 g = gpre[q];
;                         v[0] *= sigmoidf_(bf_lo(g.x)); v[1] *= sigmoidf_(bf_hi(g.x)); v[2] *= sigmoidf_(bf_lo(g.y)); v[3] *= sigmoidf_(bf_hi(g.y));
;                         v[4] *= sigmoidf_(bf_lo(g.z)); v[5] *= sigmoidf_(bf_hi(g.z)); v[6] *= sigmoidf_(bf_lo(g.w)); v[7] *= sigmoidf_(bf_hi(g.w)); }
;                     u32x4 w; w.x = pkh(v[0], v[1]); w.y = pkh(v[2], v[3]); w.z = pkh(v[4], v[5]); w.w = pkh(v[6], v[7]);
;                     *(u32x4*)(ob + (size_t)row * LDC + col) = w; }
	v_div_fixup_f32 v136, v0, v136, 1.0
	v_lshlrev_b32_e32 v0, 16, v138
	v_mul_f32_e32 v0, 0xbfb8aa3b, v0
	v_exp_f32_e32 v142, v0
	v_and_b32_e32 v0, 0xffff0000, v138
	v_mul_f32_e32 v0, 0xbfb8aa3b, v0
	v_exp_f32_e32 v143, v0
	v_pk_mul_f32 v[136:137], v[38:39], v[136:137]
	v_pk_add_f32 v[142:143], v[142:143], 1.0 op_sel_hi:[1,0]
	s_nop 0
	v_div_scale_f32 v0, s[28:29], v143, v143, 1.0
	v_rcp_f32_e32 v138, v0
	s_nop 0
	v_fma_f32 v144, -v0, v138, 1.0
	v_fmac_f32_e32 v138, v144, v138
	v_div_scale_f32 v144, vcc, 1.0, v143, 1.0
	v_mul_f32_e32 v145, v144, v138
	v_fma_f32 v146, -v0, v145, v144
	v_fmac_f32_e32 v145, v146, v138
	v_fma_f32 v0, -v0, v145, v144
	v_div_fmas_f32 v0, v0, v138, v145
	v_div_fixup_f32 v143, v0, v143, 1.0
	v_div_scale_f32 v0, s[28:29], v142, v142, 1.0
	v_rcp_f32_e32 v138, v0
	s_nop 0
	v_fma_f32 v144, -v0, v138, 1.0
	v_fmac_f32_e32 v138, v144, v138
	v_div_scale_f32 v144, vcc, 1.0, v142, 1.0
	v_mul_f32_e32 v145, v144, v138
	v_fma_f32 v146, -v0, v145, v144
	v_fmac_f32_e32 v145, v146, v138
	v_fma_f32 v0, -v0, v145, v144
	v_div_fmas_f32 v0, v0, v138, v145
	v_div_fixup_f32 v142, v0, v142, 1.0
	v_lshlrev_b32_e32 v0, 16, v139
	v_mul_f32_e32 v0, 0xbfb8aa3b, v0
	v_exp_f32_e32 v138, v0
	v_and_b32_e32 v0, 0xffff0000, v139
	v_mul_f32_e32 v0, 0xbfb8aa3b, v0
	v_exp_f32_e32 v139, v0
	v_pk_mul_f32 v[142:143], v[40:41], v[142:143]
	v_pk_add_f32 v[138:139], v[138:139], 1.0 op_sel_hi:[1,0]
	s_nop 0
	v_div_scale_f32 v0, s[28:29], v139, v139, 1.0
	v_rcp_f32_e32 v144, v0
	s_nop 0
	v_fma_f32 v145, -v0, v144, 1.0
	v_fmac_f32_e32 v144, v145, v144
	v_div_scale_f32 v145, vcc, 1.0, v139, 1.0
	v_mul_f32_e32 v146, v145, v144
	v_fma_f32 v147, -v0, v146, v145
	v_fmac_f32_e32 v146, v147, v144
	v_fma_f32 v0, -v0, v146, v145
	v_div_fmas_f32 v0, v0, v144, v146
	v_div_fixup_f32 v139, v0, v139, 1.0
	v_div_scale_f32 v0, s[28:29], v138, v138, 1.0
	v_rcp_f32_e32 v144, v0
	s_nop 0
	v_fma_f32 v145, -v0, v144, 1.0
	v_fmac_f32_e32 v144, v145, v144
	v_div_scale_f32 v145, vcc, 1.0, v138, 1.0
	v_mul_f32_e32 v146, v145, v144
	v_fma_f32 v147, -v0, v146, v145
	v_fmac_f32_e32 v146, v147, v144
	v_fma_f32 v0, -v0, v146, v145
	v_div_fmas_f32 v0, v0, v144, v146
	v_div_fixup_f32 v138, v0, v138, 1.0
	v_pk_mul_f32 v[144:145], v[42:43], v[138:139]
	v_cvt_pk_bf16_f32 v139, v136, v137
	v_lshlrev_b64 v[136:137], 12, v[154:155]
	v_lshl_add_u64 v[136:137], s[10:11], 0, v[136:137]
	v_lshlrev_b32_e32 v0, 16, v132
	v_cvt_pk_bf16_f32 v138, v140, v141
	v_cvt_pk_bf16_f32 v140, v142, v143
	v_cvt_pk_bf16_f32 v141, v144, v145
	v_lshl_add_u64 v[136:137], v[136:137], 0, v[2:3]
	v_mul_f32_e32 v0, 0xbfb8aa3b, v0
	global_store_dwordx4 v[136:137], v[138:141], off sc1
	v_add_u32_e32 v154, 0xa0, v148
	v_add_u32_e32 v148, 0xb0, v148
	v_exp_f32_e32 v138, v0
	v_and_b32_e32 v0, 0xffff0000, v132
	v_mul_f32_e32 v0, 0xbfb8aa3b, v0
	v_exp_f32_e32 v139, v0
	v_ashrrev_i32_e32 v155, 31, v154
	v_pk_add_f32 v[138:139], v[138:139], 1.0 op_sel_hi:[1,0]
	s_nop 0
	v_div_scale_f32 v0, s[28:29], v139, v139, 1.0
	v_rcp_f32_e32 v132, v0
	s_nop 0
	v_fma_f32 v140, -v0, v132, 1.0
	v_fmac_f32_e32 v132, v140, v132
	v_div_scale_f32 v140, vcc, 1.0, v139, 1.0
	v_mul_f32_e32 v141, v140, v132
	v_fma_f32 v142, -v0, v141, v140
	v_fmac_f32_e32 v141, v142, v132
	v_fma_f32 v0, -v0, v141, v140
	v_div_fmas_f32 v0, v0, v132, v141
	v_div_fixup_f32 v139, v0, v139, 1.0
	v_div_scale_f32 v0, s[28:29], v138, v138, 1.0
	v_rcp_f32_e32 v132, v0
	s_nop 0
	v_fma_f32 v140, -v0, v132, 1.0
	v_fmac_f32_e32 v132, v140, v132
	v_div_scale_f32 v140, vcc, 1.0, v138, 1.0
	v_mul_f32_e32 v141, v140, v132
	v_fma_f32 v142, -v0, v141, v140
	v_fmac_f32_e32 v141, v142, v132
	v_fma_f32 v0, -v0, v141, v140
	v_div_fmas_f32 v0, v0, v132, v141
	v_div_fixup_f32 v138, v0, v138, 1.0
	v_lshlrev_b32_e32 v0, 16, v133
	v_mul_f32_e32 v0, 0xbfb8aa3b, v0
	v_exp_f32_e32 v132, v0
	v_and_b32_e32 v0, 0xffff0000, v133
	v_mul_f32_e32 v0, 0xbfb8aa3b, v0
	v_exp_f32_e32 v133, v0
	v_pk_mul_f32 v[138:139], v[52:53], v[138:139]
	v_pk_add_f32 v[132:133], v[132:133], 1.0 op_sel_hi:[1,0]
	s_nop 0
	v_div_scale_f32 v0, s[28:29], v133, v133, 1.0
	v_rcp_f32_e32 v140, v0
	s_nop 0
	v_fma_f32 v141, -v0, v140, 1.0
	v_fmac_f32_e32 v140, v141, v140
	v_div_scale_f32 v141, vcc, 1.0, v133, 1.0
	v_mul_f32_e32 v142, v141, v140
	v_fma_f32 v143, -v0, v142, v141
	v_fmac_f32_e32 v142, v143, v140
	v_fma_f32 v0, -v0, v142, v141
	v_div_fmas_f32 v0, v0, v140, v142
	v_div_fixup_f32 v133, v0, v133, 1.0
	v_div_scale_f32 v0, s[28:29], v132, v132, 1.0
	v_rcp_f32_e32 v140, v0
	s_nop 0
	v_fma_f32 v141, -v0, v140, 1.0
	v_fmac_f32_e32 v140, v141, v140
	v_div_scale_f32 v141, vcc, 1.0, v132, 1.0
	v_mul_f32_e32 v142, v141, v140
	v_fma_f32 v143, -v0, v142, v141
	v_fmac_f32_e32 v142, v143, v140
	v_fma_f32 v0, -v0, v142, v141
	v_div_fmas_f32 v0, v0, v140, v142
	v_div_fixup_f32 v132, v0, v132, 1.0
	v_lshlrev_b32_e32 v0, 16, v134
	v_mul_f32_e32 v0, 0xbfb8aa3b, v0
	v_pk_mul_f32 v[140:141], v[54:55], v[132:133]
	v_exp_f32_e32 v132, v0
	v_and_b32_e32 v0, 0xffff0000, v134
	v_mul_f32_e32 v0, 0xbfb8aa3b, v0
	v_exp_f32_e32 v133, v0
	s_nop 0
	v_pk_add_f32 v[132:133], v[132:133], 1.0 op_sel_hi:[1,0]
	s_nop 0
	v_div_scale_f32 v0, s[28:29], v133, v133, 1.0
	v_rcp_f32_e32 v134, v0
	s_nop 0
	v_fma_f32 v142, -v0, v134, 1.0
	v_fmac_f32_e32 v134, v142, v134
	v_div_scale_f32 v142, vcc, 1.0, v133, 1.0
	v_mul_f32_e32 v143, v142, v134
	v_fma_f32 v144, -v0, v143, v142
	v_fmac_f32_e32 v143, v144, v134
	v_fma_f32 v0, -v0, v143, v142
	v_div_fmas_f32 v0, v0, v134, v143
	v_div_fixup_f32 v133, v0, v133, 1.0
	v_div_scale_f32 v0, s[28:29], v132, v132, 1.0
	v_rcp_f32_e32 v134, v0
	s_nop 0
	v_fma_f32 v142, -v0, v134, 1.0
	v_fmac_f32_e32 v134, v142, v134
; __device__ __forceinline__ unsigned pkh(float lo, float hi) { f32v2_t v; v.x = lo; v.y = hi; return __builtin_bit_cast(unsigned, __builtin_convertvector(v, bf16v2_t)); }
; __device__ __forceinline__ float bf_lo(unsigned w) { return __uint_as_float(w << 16); }
; __device__ __forceinline__ float bf_hi(unsigned w) { return __uint_as_float(w & 0xffff0000u); }
; __device__ __forceinline__ float sigmoidf_(float x) { return 1.0f / (1.0f + __expf(-x)); }
;     template <int MODE> __device__ __forceinline__ void run(const pg8::f32x4 (&acc)[2][2][4][2], const pg8::Unit& u, int wr, int wc, int fr, int fq) const {
;     ...
;                 if constexpr (MODE == 6) {
; #pragma unroll
;                     for (int q = 0; q < 4; ++q) { const int m = 2 * mp + (q >> 1), bj = q & 1; const int row = u.pm * 256 + ai * 128 + wr * 64 + m * 16 + fr, col = u.pn * 256 + bj * 128 + wc * 32 + 8 * fq;
;                         gpre[q] = *(const u32x4*)(proj + (size_t)row * NP + OFF_MG + 2 * DM + col); }
;                 }
; #pragma unroll
;                 for (int q = 0; q < 4; ++q) { const int m = 2 * mp + (q >> 1), bj = q & 1; const int row = u.pm * 256 + ai * 128 + wr * 64 + m * 16 + fr, col = u.pn * 256 + bj * 128 + wc * 32 + 8 * fq;
;                     const pg8::f32x4 t0 = acc[ai][bj][m][0], t1 = acc[ai][bj][m][1];
;                     float v[8] = {t0[0], t0[1], t0[2], t0[3], t1[0], t1[1], t1[2], t1[3]};
;                     if constexpr (MODE == 5) {
; #pragma unroll
;                         for (int e = 0; e < 8; ++e) { const float r = fmaxf(v[e], 0.f); v[e] = r * r; }
;                     }
;                     if constexpr (MODE == 6) { const u32x4 g = gpre[q];
;                         v[0] *= sigmoidf_(bf_lo(g.x)); v[1] *= sigmoidf_(bf_hi(g.x)); v[2] *= sigmoidf_(bf_lo(g.y)); v[3] *= sigmoidf_(bf_hi(g.y));
;                         v[4] *= sigmoidf_(bf_lo(g.z)); v[5] *= sigmoidf_(bf_hi(g.z)); v[6] *= sigmoidf_(bf_lo(g.w)); v[7] *= sigmoidf_(bf_hi(g.w)); }
;                     u32x4 w; w.x = pkh(v[0], v[1]); w.y = pkh(v[2], v[3]); w.z = pkh(v[4], v[5]); w.w = pkh(v[6], v[7]);
;                     *(u32x4*)(ob + (size_t)row * LDC + col) = w; }
	v_div_scale_f32 v142, vcc, 1.0, v132, 1.0
	v_mul_f32_e32 v143, v142, v134
	v_fma_f32 v144, -v0, v143, v142
	v_fmac_f32_e32 v143, v144, v134
	v_fma_f32 v0, -v0, v143, v142
	v_div_fmas_f32 v0, v0, v134, v143
	v_div_fixup_f32 v132, v0, v132, 1.0
	v_lshlrev_b32_e32 v0, 16, v135
	v_mul_f32_e32 v0, 0xbfb8aa3b, v0
	v_pk_mul_f32 v[142:143], v[56:57], v[132:133]
	v_exp_f32_e32 v132, v0
	v_and_b32_e32 v0, 0xffff0000, v135
	v_mul_f32_e32 v0, 0xbfb8aa3b, v0
	v_exp_f32_e32 v133, v0
	s_nop 0
	v_pk_add_f32 v[132:133], v[132:133], 1.0 op_sel_hi:[1,0]
	s_nop 0
	v_div_scale_f32 v0, s[28:29], v133, v133, 1.0
	v_rcp_f32_e32 v134, v0
	s_nop 0
	v_fma_f32 v135, -v0, v134, 1.0
	v_fmac_f32_e32 v134, v135, v134
	v_div_scale_f32 v135, vcc, 1.0, v133, 1.0
	v_mul_f32_e32 v144, v135, v134
	v_fma_f32 v145, -v0, v144, v135
	v_fmac_f32_e32 v144, v145, v134
	v_fma_f32 v0, -v0, v144, v135
	v_div_fmas_f32 v0, v0, v134, v144
	v_div_fixup_f32 v133, v0, v133, 1.0
	v_div_scale_f32 v0, s[28:29], v132, v132, 1.0
	v_rcp_f32_e32 v134, v0
	s_nop 0
	v_fma_f32 v135, -v0, v134, 1.0
	v_fmac_f32_e32 v134, v135, v134
	v_div_scale_f32 v135, vcc, 1.0, v132, 1.0
	v_mul_f32_e32 v144, v135, v134
	v_fma_f32 v145, -v0, v144, v135
	v_fmac_f32_e32 v144, v145, v134
	v_fma_f32 v0, -v0, v144, v135
	v_div_fmas_f32 v0, v0, v134, v144
	v_div_fixup_f32 v132, v0, v132, 1.0
	v_pk_mul_f32 v[144:145], v[58:59], v[132:133]
	v_cvt_pk_bf16_f32 v132, v138, v139
	v_cvt_pk_bf16_f32 v133, v140, v141
	v_cvt_pk_bf16_f32 v134, v142, v143
	v_cvt_pk_bf16_f32 v135, v144, v145
	global_store_dwordx4 v[136:137], v[132:135], off offset:256 sc1
	s_nop 1
	v_mad_i64_i32 v[132:133], s[28:29], v154, s76, v[150:151]
	v_lshl_add_u64 v[132:133], v[132:133], 0, s[30:31]
	v_lshl_add_u64 v[134:135], v[132:133], 0, v[2:3]
	global_load_dwordx4 v[144:147], v[134:135], off
	v_lshl_add_u64 v[132:133], v[132:133], 0, v[152:153]
	global_load_dwordx4 v[140:143], v[132:133], off
	v_mad_i64_i32 v[132:133], s[28:29], v148, s76, v[150:151]
	v_lshl_add_u64 v[132:133], v[132:133], 0, s[30:31]
	v_lshl_add_u64 v[134:135], v[132:133], 0, v[2:3]
	v_lshl_add_u64 v[132:133], v[132:133], 0, v[152:153]
	global_load_dwordx4 v[136:139], v[134:135], off
	s_waitcnt vmcnt(0)
	v_lshlrev_b32_e32 v0, 16, v144
	v_mul_f32_e32 v0, 0xbfb8aa3b, v0
	v_exp_f32_e32 v150, v0
	v_and_b32_e32 v0, 0xffff0000, v144
	v_mul_f32_e32 v0, 0xbfb8aa3b, v0
	v_exp_f32_e32 v151, v0
	global_load_dwordx4 v[132:135], v[132:133], off
	v_pk_add_f32 v[150:151], v[150:151], 1.0 op_sel_hi:[1,0]
	s_nop 0
	v_div_scale_f32 v0, s[28:29], v151, v151, 1.0
	v_rcp_f32_e32 v144, v0
	s_nop 0
	v_fma_f32 v149, -v0, v144, 1.0
	v_fmac_f32_e32 v144, v149, v144
	v_div_scale_f32 v149, vcc, 1.0, v151, 1.0
	v_mul_f32_e32 v152, v149, v144
	v_fma_f32 v153, -v0, v152, v149
	v_fmac_f32_e32 v152, v153, v144
	v_fma_f32 v0, -v0, v152, v149
	v_div_fmas_f32 v0, v0, v144, v152
	v_div_fixup_f32 v151, v0, v151, 1.0
	v_div_scale_f32 v0, s[28:29], v150, v150, 1.0
	v_rcp_f32_e32 v144, v0
	s_nop 0
	v_fma_f32 v149, -v0, v144, 1.0
	v_fmac_f32_e32 v144, v149, v144
	v_div_scale_f32 v149, vcc, 1.0, v150, 1.0
	v_mul_f32_e32 v152, v149, v144
	v_fma_f32 v153, -v0, v152, v149
	v_fmac_f32_e32 v152, v153, v144
	v_fma_f32 v0, -v0, v152, v149
	v_div_fmas_f32 v0, v0, v144, v152
	v_div_fixup_f32 v150, v0, v150, 1.0
	v_lshlrev_b32_e32 v0, 16, v145
	v_mul_f32_e32 v0, 0xbfb8aa3b, v0
	v_exp_f32_e32 v144, v0
	v_and_b32_e32 v0, 0xffff0000, v145
	v_mul_f32_e32 v0, 0xbfb8aa3b, v0
	v_exp_f32_e32 v145, v0
	v_pk_mul_f32 v[150:151], v[20:21], v[150:151]
	v_pk_add_f32 v[144:145], v[144:145], 1.0 op_sel_hi:[1,0]
	s_nop 0
	v_div_scale_f32 v0, s[28:29], v145, v145, 1.0
	v_rcp_f32_e32 v149, v0
	v_cvt_pk_bf16_f32 v150, v150, v151
	v_fma_f32 v152, -v0, v149, 1.0
	v_fmac_f32_e32 v149, v152, v149
	v_div_scale_f32 v152, vcc, 1.0, v145, 1.0
	v_mul_f32_e32 v153, v152, v149
	v_fma_f32 v156, -v0, v153, v152
	v_fmac_f32_e32 v153, v156, v149
	v_fma_f32 v0, -v0, v153, v152
	v_div_fmas_f32 v0, v0, v149, v153
	v_div_fixup_f32 v145, v0, v145, 1.0
	v_div_scale_f32 v0, s[28:29], v144, v144, 1.0
	v_rcp_f32_e32 v149, v0
	s_nop 0
	v_fma_f32 v152, -v0, v149, 1.0
	v_fmac_f32_e32 v149, v152, v149
	v_div_scale_f32 v152, vcc, 1.0, v144, 1.0
	v_mul_f32_e32 v153, v152, v149
	v_fma_f32 v156, -v0, v153, v152
	v_fmac_f32_e32 v153, v156, v149
	v_fma_f32 v0, -v0, v153, v152
	v_div_fmas_f32 v0, v0, v149, v153
	v_div_fixup_f32 v144, v0, v144, 1.0
	v_lshlrev_b32_e32 v0, 16, v146
	v_mul_f32_e32 v0, 0xbfb8aa3b, v0
	v_exp_f32_e32 v152, v0
	v_and_b32_e32 v0, 0xffff0000, v146
	v_mul_f32_e32 v0, 0xbfb8aa3b, v0
	v_exp_f32_e32 v153, v0
	v_pk_mul_f32 v[144:145], v[22:23], v[144:145]
	v_pk_add_f32 v[152:153], v[152:153], 1.0 op_sel_hi:[1,0]
	s_nop 0
	v_div_scale_f32 v0, s[28:29], v153, v153, 1.0
	v_rcp_f32_e32 v146, v0
	v_cvt_pk_bf16_f32 v151, v144, v145
	v_lshlrev_b64 v[144:145], 12, v[154:155]
	v_lshl_add_u64 v[144:145], s[10:11], 0, v[144:145]
	v_fma_f32 v149, -v0, v146, 1.0
	v_fmac_f32_e32 v146, v149, v146
	v_div_scale_f32 v149, vcc, 1.0, v153, 1.0
	v_mul_f32_e32 v156, v149, v146
	v_fma_f32 v157, -v0, v156, v149
	v_fmac_f32_e32 v156, v157, v146
	v_fma_f32 v0, -v0, v156, v149
	v_div_fmas_f32 v0, v0, v146, v156
	v_div_fixup_f32 v153, v0, v153, 1.0
	v_div_scale_f32 v0, s[28:29], v152, v152, 1.0
	v_rcp_f32_e32 v146, v0
	v_lshl_add_u64 v[144:145], v[144:145], 0, v[2:3]
	v_fma_f32 v149, -v0, v146, 1.0
	v_fmac_f32_e32 v146, v149, v146
	v_div_scale_f32 v149, vcc, 1.0, v152, 1.0
	v_mul_f32_e32 v156, v149, v146
	v_fma_f32 v157, -v0, v156, v149
	v_fmac_f32_e32 v156, v157, v146
	v_fma_f32 v0, -v0, v156, v149
	v_div_fmas_f32 v0, v0, v146, v156
	v_div_fixup_f32 v152, v0, v152, 1.0
	v_lshlrev_b32_e32 v0, 16, v147
; __device__ __forceinline__ unsigned pkh(float lo, float hi) { f32v2_t v; v.x = lo; v.y = hi; return __builtin_bit_cast(unsigned, __builtin_convertvector(v, bf16v2_t)); }
; __device__ __forceinline__ float bf_lo(unsigned w) { return __uint_as_float(w << 16); }
; __device__ __forceinline__ float bf_hi(unsigned w) { return __uint_as_float(w & 0xffff0000u); }
; __device__ __forceinline__ float sigmoidf_(float x) { return 1.0f / (1.0f + __expf(-x)); }
;     template <int MODE> __device__ __forceinline__ void run(const pg8::f32x4 (&acc)[2][2][4][2], const pg8::Unit& u, int wr, int wc, int fr, int fq) const {
;     ...
;                 if constexpr (MODE == 6) {
; #pragma unroll
;                     for (int q = 0; q < 4; ++q) { const int m = 2 * mp + (q >> 1), bj = q & 1; const int row = u.pm * 256 + ai * 128 + wr * 64 + m * 16 + fr, col = u.pn * 256 + bj * 128 + wc * 32 + 8 * fq;
;                         gpre[q] = *(const u32x4*)(proj + (size_t)row * NP + OFF_MG + 2 * DM + col); }
;                 }
; #pragma unroll
;                 for (int q = 0; q < 4; ++q) { const int m = 2 * mp + (q >> 1), bj = q & 1; const int row = u.pm * 256 + ai * 128 + wr * 64 + m * 16 + fr, col = u.pn * 256 + bj * 128 + wc * 32 + 8 * fq;
;                     const pg8::f32x4 t0 = acc[ai][bj][m][0], t1 = acc[ai][bj][m][1];
;                     float v[8] = {t0[0], t0[1], t0[2], t0[3], t1[0], t1[1], t1[2], t1[3]};
;                     if constexpr (MODE == 5) {
; #pragma unroll
;                         for (int e = 0; e < 8; ++e) { const float r = fmaxf(v[e], 0.f); v[e] = r * r; }
;                     }
;                     if constexpr (MODE == 6) { const u32x4 g = gpre[q];
;                         v[0] *= sigmoidf_(bf_lo(g.x)); v[1] *= sigmoidf_(bf_hi(g.x)); v[2] *= sigmoidf_(bf_lo(g.y)); v[3] *= sigmoidf_(bf_hi(g.y));
;                         v[4] *= sigmoidf_(bf_lo(g.z)); v[5] *= sigmoidf_(bf_hi(g.z)); v[6] *= sigmoidf_(bf_lo(g.w)); v[7] *= sigmoidf_(bf_hi(g.w)); }
;                     u32x4 w; w.x = pkh(v[0], v[1]); w.y = pkh(v[2], v[3]); w.z = pkh(v[4], v[5]); w.w = pkh(v[6], v[7]);
;                     *(u32x4*)(ob + (size_t)row * LDC + col) = w; }
	v_mul_f32_e32 v0, 0xbfb8aa3b, v0
	v_exp_f32_e32 v146, v0
	v_and_b32_e32 v0, 0xffff0000, v147
	v_mul_f32_e32 v0, 0xbfb8aa3b, v0
	v_exp_f32_e32 v147, v0
	v_pk_mul_f32 v[152:153], v[24:25], v[152:153]
	v_pk_add_f32 v[146:147], v[146:147], 1.0 op_sel_hi:[1,0]
	s_nop 0
	v_div_scale_f32 v0, s[28:29], v147, v147, 1.0
	v_rcp_f32_e32 v149, v0
	v_cvt_pk_bf16_f32 v152, v152, v153
	v_fma_f32 v156, -v0, v149, 1.0
	v_fmac_f32_e32 v149, v156, v149
	v_div_scale_f32 v156, vcc, 1.0, v147, 1.0
	v_mul_f32_e32 v157, v156, v149
	v_fma_f32 v158, -v0, v157, v156
	v_fmac_f32_e32 v157, v158, v149
	v_fma_f32 v0, -v0, v157, v156
	v_div_fmas_f32 v0, v0, v149, v157
	v_div_fixup_f32 v147, v0, v147, 1.0
	v_div_scale_f32 v0, s[28:29], v146, v146, 1.0
	v_rcp_f32_e32 v149, v0
	s_nop 0
	v_fma_f32 v156, -v0, v149, 1.0
	v_fmac_f32_e32 v149, v156, v149
	v_div_scale_f32 v156, vcc, 1.0, v146, 1.0
	v_mul_f32_e32 v157, v156, v149
	v_fma_f32 v158, -v0, v157, v156
	v_fmac_f32_e32 v157, v158, v149
	v_fma_f32 v0, -v0, v157, v156
	v_div_fmas_f32 v0, v0, v149, v157
	v_div_fixup_f32 v146, v0, v146, 1.0
	v_lshlrev_b32_e32 v0, 16, v140
	v_pk_mul_f32 v[146:147], v[26:27], v[146:147]
	v_mul_f32_e32 v0, 0xbfb8aa3b, v0
	v_cvt_pk_bf16_f32 v153, v146, v147
	v_exp_f32_e32 v146, v0
	v_and_b32_e32 v0, 0xffff0000, v140
	v_mul_f32_e32 v0, 0xbfb8aa3b, v0
	v_exp_f32_e32 v147, v0
	global_store_dwordx4 v[144:145], v[150:153], off sc1
	v_pk_add_f32 v[146:147], v[146:147], 1.0 op_sel_hi:[1,0]
	s_nop 0
	v_div_scale_f32 v0, s[28:29], v147, v147, 1.0
	v_rcp_f32_e32 v140, v0
	s_nop 0
	v_fma_f32 v149, -v0, v140, 1.0
	v_fmac_f32_e32 v140, v149, v140
	v_div_scale_f32 v149, vcc, 1.0, v147, 1.0
	v_mul_f32_e32 v150, v149, v140
	v_fma_f32 v151, -v0, v150, v149
	v_fmac_f32_e32 v150, v151, v140
	v_fma_f32 v0, -v0, v150, v149
	v_div_fmas_f32 v0, v0, v140, v150
	v_div_fixup_f32 v147, v0, v147, 1.0
	v_div_scale_f32 v0, s[28:29], v146, v146, 1.0
	v_rcp_f32_e32 v140, v0
	s_nop 0
	v_fma_f32 v149, -v0, v140, 1.0
	v_fmac_f32_e32 v140, v149, v140
	v_div_scale_f32 v149, vcc, 1.0, v146, 1.0
	v_mul_f32_e32 v150, v149, v140
	v_fma_f32 v151, -v0, v150, v149
	v_fmac_f32_e32 v150, v151, v140
	v_fma_f32 v0, -v0, v150, v149
	v_div_fmas_f32 v0, v0, v140, v150
	v_div_fixup_f32 v146, v0, v146, 1.0
	v_lshlrev_b32_e32 v0, 16, v141
	v_mul_f32_e32 v0, 0xbfb8aa3b, v0
	v_exp_f32_e32 v140, v0
	v_and_b32_e32 v0, 0xffff0000, v141
	v_mul_f32_e32 v0, 0xbfb8aa3b, v0
	v_exp_f32_e32 v141, v0
	v_pk_mul_f32 v[146:147], v[28:29], v[146:147]
	v_pk_add_f32 v[140:141], v[140:141], 1.0 op_sel_hi:[1,0]
	s_nop 0
	v_div_scale_f32 v0, s[28:29], v141, v141, 1.0
	v_rcp_f32_e32 v149, v0
	s_nop 0
	v_fma_f32 v150, -v0, v149, 1.0
	v_fmac_f32_e32 v149, v150, v149
	v_div_scale_f32 v150, vcc, 1.0, v141, 1.0
	v_mul_f32_e32 v151, v150, v149
	v_fma_f32 v152, -v0, v151, v150
	v_fmac_f32_e32 v151, v152, v149
	v_fma_f32 v0, -v0, v151, v150
	v_div_fmas_f32 v0, v0, v149, v151
	v_div_fixup_f32 v141, v0, v141, 1.0
	v_div_scale_f32 v0, s[28:29], v140, v140, 1.0
	v_rcp_f32_e32 v149, v0
	s_nop 0
	v_fma_f32 v150, -v0, v149, 1.0
	v_fmac_f32_e32 v149, v150, v149
	v_div_scale_f32 v150, vcc, 1.0, v140, 1.0
	v_mul_f32_e32 v151, v150, v149
	v_fma_f32 v152, -v0, v151, v150
	v_fmac_f32_e32 v151, v152, v149
	v_fma_f32 v0, -v0, v151, v150
	v_div_fmas_f32 v0, v0, v149, v151
	v_div_fixup_f32 v140, v0, v140, 1.0
	v_lshlrev_b32_e32 v0, 16, v142
	v_mul_f32_e32 v0, 0xbfb8aa3b, v0
	v_pk_mul_f32 v[150:151], v[30:31], v[140:141]
	v_exp_f32_e32 v140, v0
	v_and_b32_e32 v0, 0xffff0000, v142
	v_mul_f32_e32 v0, 0xbfb8aa3b, v0
	v_exp_f32_e32 v141, v0
	s_nop 0
	v_pk_add_f32 v[140:141], v[140:141], 1.0 op_sel_hi:[1,0]
	s_nop 0
	v_div_scale_f32 v0, s[28:29], v141, v141, 1.0
	v_rcp_f32_e32 v142, v0
	s_nop 0
	v_fma_f32 v149, -v0, v142, 1.0
	v_fmac_f32_e32 v142, v149, v142
	v_div_scale_f32 v149, vcc, 1.0, v141, 1.0
	v_mul_f32_e32 v152, v149, v142
	v_fma_f32 v153, -v0, v152, v149
	v_fmac_f32_e32 v152, v153, v142
	v_fma_f32 v0, -v0, v152, v149
	v_div_fmas_f32 v0, v0, v142, v152
	v_div_fixup_f32 v141, v0, v141, 1.0
	v_div_scale_f32 v0, s[28:29], v140, v140, 1.0
	v_rcp_f32_e32 v142, v0
	s_nop 0
	v_fma_f32 v149, -v0, v142, 1.0
	v_fmac_f32_e32 v142, v149, v142
	v_div_scale_f32 v149, vcc, 1.0, v140, 1.0
	v_mul_f32_e32 v152, v149, v142
	v_fma_f32 v153, -v0, v152, v149
	v_fmac_f32_e32 v152, v153, v142
	v_fma_f32 v0, -v0, v152, v149
	v_div_fmas_f32 v0, v0, v142, v152
	v_div_fixup_f32 v140, v0, v140, 1.0
	v_lshlrev_b32_e32 v0, 16, v143
	v_mul_f32_e32 v0, 0xbfb8aa3b, v0
	v_pk_mul_f32 v[152:153], v[32:33], v[140:141]
	v_exp_f32_e32 v140, v0
	v_and_b32_e32 v0, 0xffff0000, v143
	v_mul_f32_e32 v0, 0xbfb8aa3b, v0
	v_exp_f32_e32 v141, v0
	s_nop 0
	v_pk_add_f32 v[140:141], v[140:141], 1.0 op_sel_hi:[1,0]
	s_nop 0
	v_div_scale_f32 v0, s[28:29], v141, v141, 1.0
	v_rcp_f32_e32 v142, v0
	s_nop 0
	v_fma_f32 v143, -v0, v142, 1.0
	v_fmac_f32_e32 v142, v143, v142
	v_div_scale_f32 v143, vcc, 1.0, v141, 1.0
	v_mul_f32_e32 v149, v143, v142
	v_fma_f32 v154, -v0, v149, v143
	v_fmac_f32_e32 v149, v154, v142
	v_fma_f32 v0, -v0, v149, v143
	v_div_fmas_f32 v0, v0, v142, v149
	v_div_fixup_f32 v141, v0, v141, 1.0
	v_div_scale_f32 v0, s[28:29], v140, v140, 1.0
	v_rcp_f32_e32 v142, v0
	s_nop 0
	v_fma_f32 v143, -v0, v142, 1.0
	v_fmac_f32_e32 v142, v143, v142
	v_div_scale_f32 v143, vcc, 1.0, v140, 1.0
	v_mul_f32_e32 v149, v143, v142
	v_fma_f32 v154, -v0, v149, v143
	v_fmac_f32_e32 v149, v154, v142
	v_fma_f32 v0, -v0, v149, v143
	v_div_fmas_f32 v0, v0, v142, v149
	v_div_fixup_f32 v140, v0, v140, 1.0
	v_pk_mul_f32 v[154:155], v[34:35], v[140:141]
	v_lshlrev_b32_e32 v0, 16, v136
	v_cvt_pk_bf16_f32 v140, v146, v147
	v_cvt_pk_bf16_f32 v141, v150, v151
; __device__ __forceinline__ unsigned pkh(float lo, float hi) { f32v2_t v; v.x = lo; v.y = hi; return __builtin_bit_cast(unsigned, __builtin_convertvector(v, bf16v2_t)); }
; __device__ __forceinline__ float bf_lo(unsigned w) { return __uint_as_float(w << 16); }
; __device__ __forceinline__ float bf_hi(unsigned w) { return __uint_as_float(w & 0xffff0000u); }
; __device__ __forceinline__ float sigmoidf_(float x) { return 1.0f / (1.0f + __expf(-x)); }
;     template <int MODE> __device__ __forceinline__ void run(const pg8::f32x4 (&acc)[2][2][4][2], const pg8::Unit& u, int wr, int wc, int fr, int fq) const {
;     ...
;                 if constexpr (MODE == 6) {
; #pragma unroll
;                     for (int q = 0; q < 4; ++q) { const int m = 2 * mp + (q >> 1), bj = q & 1; const int row = u.pm * 256 + ai * 128 + wr * 64 + m * 16 + fr, col = u.pn * 256 + bj * 128 + wc * 32 + 8 * fq;
;                         gpre[q] = *(const u32x4*)(proj + (size_t)row * NP + OFF_MG + 2 * DM + col); }
;                 }
; #pragma unroll
;                 for (int q = 0; q < 4; ++q) { const int m = 2 * mp + (q >> 1), bj = q & 1; const int row = u.pm * 256 + ai * 128 + wr * 64 + m * 16 + fr, col = u.pn * 256 + bj * 128 + wc * 32 + 8 * fq;
;                     const pg8::f32x4 t0 = acc[ai][bj][m][0], t1 = acc[ai][bj][m][1];
;                     float v[8] = {t0[0], t0[1], t0[2], t0[3], t1[0], t1[1], t1[2], t1[3]};
;                     if constexpr (MODE == 5) {
; #pragma unroll
;                         for (int e = 0; e < 8; ++e) { const float r = fmaxf(v[e], 0.f); v[e] = r * r; }
;                     }
;                     if constexpr (MODE == 6) { const u32x4 g = gpre[q];
;                         v[0] *= sigmoidf_(bf_lo(g.x)); v[1] *= sigmoidf_(bf_hi(g.x)); v[2] *= sigmoidf_(bf_lo(g.y)); v[3] *= sigmoidf_(bf_hi(g.y));
;                         v[4] *= sigmoidf_(bf_lo(g.z)); v[5] *= sigmoidf_(bf_hi(g.z)); v[6] *= sigmoidf_(bf_lo(g.w)); v[7] *= sigmoidf_(bf_hi(g.w)); }
;                     u32x4 w; w.x = pkh(v[0], v[1]); w.y = pkh(v[2], v[3]); w.z = pkh(v[4], v[5]); w.w = pkh(v[6], v[7]);
;                     *(u32x4*)(ob + (size_t)row * LDC + col) = w; }
	v_cvt_pk_bf16_f32 v142, v152, v153
	v_cvt_pk_bf16_f32 v143, v154, v155
	v_mul_f32_e32 v0, 0xbfb8aa3b, v0
	global_store_dwordx4 v[144:145], v[140:143], off offset:256 sc1
	v_ashrrev_i32_e32 v149, 31, v148
	s_nop 0
	v_exp_f32_e32 v140, v0
	v_and_b32_e32 v0, 0xffff0000, v136
	v_mul_f32_e32 v0, 0xbfb8aa3b, v0
	v_exp_f32_e32 v141, v0
	s_nop 0
	v_pk_add_f32 v[140:141], v[140:141], 1.0 op_sel_hi:[1,0]
	s_nop 0
	v_div_scale_f32 v0, s[28:29], v141, v141, 1.0
	v_rcp_f32_e32 v136, v0
	s_nop 0
	v_fma_f32 v142, -v0, v136, 1.0
	v_fmac_f32_e32 v136, v142, v136
	v_div_scale_f32 v142, vcc, 1.0, v141, 1.0
	v_mul_f32_e32 v143, v142, v136
	v_fma_f32 v144, -v0, v143, v142
	v_fmac_f32_e32 v143, v144, v136
	v_fma_f32 v0, -v0, v143, v142
	v_div_fmas_f32 v0, v0, v136, v143
	v_div_fixup_f32 v141, v0, v141, 1.0
	v_div_scale_f32 v0, s[28:29], v140, v140, 1.0
	v_rcp_f32_e32 v136, v0
	s_nop 0
	v_fma_f32 v142, -v0, v136, 1.0
	v_fmac_f32_e32 v136, v142, v136
	v_div_scale_f32 v142, vcc, 1.0, v140, 1.0
	v_mul_f32_e32 v143, v142, v136
	v_fma_f32 v144, -v0, v143, v142
	v_fmac_f32_e32 v143, v144, v136
	v_fma_f32 v0, -v0, v143, v142
	v_div_fmas_f32 v0, v0, v136, v143
	v_div_fixup_f32 v140, v0, v140, 1.0
	v_lshlrev_b32_e32 v0, 16, v137
	v_mul_f32_e32 v0, 0xbfb8aa3b, v0
	v_exp_f32_e32 v136, v0
	v_and_b32_e32 v0, 0xffff0000, v137
	v_mul_f32_e32 v0, 0xbfb8aa3b, v0
	v_exp_f32_e32 v137, v0
	v_pk_mul_f32 v[140:141], v[4:5], v[140:141]
	v_pk_add_f32 v[136:137], v[136:137], 1.0 op_sel_hi:[1,0]
	s_nop 0
	v_div_scale_f32 v0, s[28:29], v137, v137, 1.0
	v_rcp_f32_e32 v142, v0
	s_nop 0
	v_fma_f32 v143, -v0, v142, 1.0
	v_fmac_f32_e32 v142, v143, v142
	v_div_scale_f32 v143, vcc, 1.0, v137, 1.0
	v_mul_f32_e32 v144, v143, v142
	v_fma_f32 v145, -v0, v144, v143
	v_fmac_f32_e32 v144, v145, v142
	v_fma_f32 v0, -v0, v144, v143
	v_div_fmas_f32 v0, v0, v142, v144
	v_div_fixup_f32 v137, v0, v137, 1.0
	v_div_scale_f32 v0, s[28:29], v136, v136, 1.0
	v_rcp_f32_e32 v142, v0
	s_nop 0
	v_fma_f32 v143, -v0, v142, 1.0
	v_fmac_f32_e32 v142, v143, v142
	v_div_scale_f32 v143, vcc, 1.0, v136, 1.0
	v_mul_f32_e32 v144, v143, v142
	v_fma_f32 v145, -v0, v144, v143
	v_fmac_f32_e32 v144, v145, v142
	v_fma_f32 v0, -v0, v144, v143
	v_div_fmas_f32 v0, v0, v142, v144
	v_div_fixup_f32 v136, v0, v136, 1.0
	v_lshlrev_b32_e32 v0, 16, v138
	v_mul_f32_e32 v0, 0xbfb8aa3b, v0
	v_pk_mul_f32 v[142:143], v[6:7], v[136:137]
	v_exp_f32_e32 v136, v0
	v_and_b32_e32 v0, 0xffff0000, v138
	v_mul_f32_e32 v0, 0xbfb8aa3b, v0
	v_exp_f32_e32 v137, v0
	s_nop 0
	v_pk_add_f32 v[136:137], v[136:137], 1.0 op_sel_hi:[1,0]
	s_nop 0
	v_div_scale_f32 v0, s[28:29], v137, v137, 1.0
	v_rcp_f32_e32 v138, v0
	s_nop 0
	v_fma_f32 v144, -v0, v138, 1.0
	v_fmac_f32_e32 v138, v144, v138
	v_div_scale_f32 v144, vcc, 1.0, v137, 1.0
	v_mul_f32_e32 v145, v144, v138
	v_fma_f32 v146, -v0, v145, v144
	v_fmac_f32_e32 v145, v146, v138
	v_fma_f32 v0, -v0, v145, v144
	v_div_fmas_f32 v0, v0, v138, v145
	v_div_fixup_f32 v137, v0, v137, 1.0
	v_div_scale_f32 v0, s[28:29], v136, v136, 1.0
	v_rcp_f32_e32 v138, v0
	s_nop 0
	v_fma_f32 v144, -v0, v138, 1.0
	v_fmac_f32_e32 v138, v144, v138
	v_div_scale_f32 v144, vcc, 1.0, v136, 1.0
	v_mul_f32_e32 v145, v144, v138
	v_fma_f32 v146, -v0, v145, v144
	v_fmac_f32_e32 v145, v146, v138
	v_fma_f32 v0, -v0, v145, v144
	v_div_fmas_f32 v0, v0, v138, v145
	v_div_fixup_f32 v136, v0, v136, 1.0
	v_lshlrev_b32_e32 v0, 16, v139
	v_mul_f32_e32 v0, 0xbfb8aa3b, v0
	v_pk_mul_f32 v[144:145], v[8:9], v[136:137]
	v_exp_f32_e32 v136, v0
	v_and_b32_e32 v0, 0xffff0000, v139
	v_mul_f32_e32 v0, 0xbfb8aa3b, v0
	v_exp_f32_e32 v137, v0
	s_nop 0
	v_pk_add_f32 v[136:137], v[136:137], 1.0 op_sel_hi:[1,0]
	s_nop 0
	v_div_scale_f32 v0, s[28:29], v137, v137, 1.0
	v_rcp_f32_e32 v138, v0
	s_nop 0
	v_fma_f32 v139, -v0, v138, 1.0
	v_fmac_f32_e32 v138, v139, v138
	v_div_scale_f32 v139, vcc, 1.0, v137, 1.0
	v_mul_f32_e32 v146, v139, v138
	v_fma_f32 v147, -v0, v146, v139
	v_fmac_f32_e32 v146, v147, v138
	v_fma_f32 v0, -v0, v146, v139
	v_div_fmas_f32 v0, v0, v138, v146
	v_div_fixup_f32 v137, v0, v137, 1.0
	v_div_scale_f32 v0, s[28:29], v136, v136, 1.0
	v_rcp_f32_e32 v138, v0
	s_nop 0
	v_fma_f32 v139, -v0, v138, 1.0
	v_fmac_f32_e32 v138, v139, v138
	v_div_scale_f32 v139, vcc, 1.0, v136, 1.0
	v_mul_f32_e32 v146, v139, v138
	v_fma_f32 v147, -v0, v146, v139
	v_fmac_f32_e32 v146, v147, v138
	v_fma_f32 v0, -v0, v146, v139
	v_div_fmas_f32 v0, v0, v138, v146
	v_div_fixup_f32 v136, v0, v136, 1.0
	v_pk_mul_f32 v[146:147], v[10:11], v[136:137]
	v_cvt_pk_bf16_f32 v136, v140, v141
	v_lshlrev_b64 v[140:141], 12, v[148:149]
	v_lshl_add_u64 v[140:141], s[10:11], 0, v[140:141]
	s_waitcnt vmcnt(0)
; __device__ __forceinline__ unsigned pkh(float lo, float hi) { f32v2_t v; v.x = lo; v.y = hi; return __builtin_bit_cast(unsigned, __builtin_convertvector(v, bf16v2_t)); }
; __device__ __forceinline__ float bf_lo(unsigned w) { return __uint_as_float(w << 16); }
; __device__ __forceinline__ float bf_hi(unsigned w) { return __uint_as_float(w & 0xffff0000u); }
; __device__ __forceinline__ float sigmoidf_(float x) { return 1.0f / (1.0f + __expf(-x)); }
;     template <int MODE> __device__ __forceinline__ void run(const pg8::f32x4 (&acc)[2][2][4][2], const pg8::Unit& u, int wr, int wc, int fr, int fq) const {
;     ...
;                 if constexpr (MODE == 6) {
; #pragma unroll
;                     for (int q = 0; q < 4; ++q) { const int m = 2 * mp + (q >> 1), bj = q & 1; const int row = u.pm * 256 + ai * 128 + wr * 64 + m * 16 + fr, col = u.pn * 256 + bj * 128 + wc * 32 + 8 * fq;
;                         gpre[q] = *(const u32x4*)(proj + (size_t)row * NP + OFF_MG + 2 * DM + col); }
;                 }
; #pragma unroll
;                 for (int q = 0; q < 4; ++q) { const int m = 2 * mp + (q >> 1), bj = q & 1; const int row = u.pm * 256 + ai * 128 + wr * 64 + m * 16 + fr, col = u.pn * 256 + bj * 128 + wc * 32 + 8 * fq;
;                     const pg8::f32x4 t0 = acc[ai][bj][m][0], t1 = acc[ai][bj][m][1];
;                     float v[8] = {t0[0], t0[1], t0[2], t0[3], t1[0], t1[1], t1[2], t1[3]};
;                     if constexpr (MODE == 5) {
; #pragma unroll
;                         for (int e = 0; e < 8; ++e) { const float r = fmaxf(v[e], 0.f); v[e] = r * r; }
;                     }
;                     if constexpr (MODE == 6) { const u32x4 g = gpre[q];
;                         v[0] *= sigmoidf_(bf_lo(g.x)); v[1] *= sigmoidf_(bf_hi(g.x)); v[2] *= sigmoidf_(bf_lo(g.y)); v[3] *= sigmoidf_(bf_hi(g.y));
;                         v[4] *= sigmoidf_(bf_lo(g.z)); v[5] *= sigmoidf_(bf_hi(g.z)); v[6] *= sigmoidf_(bf_lo(g.w)); v[7] *= sigmoidf_(bf_hi(g.w)); }
;                     u32x4 w; w.x = pkh(v[0], v[1]); w.y = pkh(v[2], v[3]); w.z = pkh(v[4], v[5]); w.w = pkh(v[6], v[7]);
;                     *(u32x4*)(ob + (size_t)row * LDC + col) = w; }
	v_lshlrev_b32_e32 v0, 16, v132
	v_cvt_pk_bf16_f32 v137, v142, v143
	v_cvt_pk_bf16_f32 v138, v144, v145
	v_cvt_pk_bf16_f32 v139, v146, v147
	v_lshl_add_u64 v[2:3], v[140:141], 0, v[2:3]
	v_mul_f32_e32 v0, 0xbfb8aa3b, v0
	global_store_dwordx4 v[2:3], v[136:139], off sc1
	s_nop 1
	v_exp_f32_e32 v136, v0
	v_and_b32_e32 v0, 0xffff0000, v132
	v_mul_f32_e32 v0, 0xbfb8aa3b, v0
	v_exp_f32_e32 v137, v0
	s_nop 0
	v_pk_add_f32 v[136:137], v[136:137], 1.0 op_sel_hi:[1,0]
	s_nop 0
	v_div_scale_f32 v0, s[28:29], v137, v137, 1.0
	v_rcp_f32_e32 v132, v0
	s_nop 0
	v_fma_f32 v138, -v0, v132, 1.0
	v_fmac_f32_e32 v132, v138, v132
	v_div_scale_f32 v138, vcc, 1.0, v137, 1.0
	v_mul_f32_e32 v139, v138, v132
	v_fma_f32 v140, -v0, v139, v138
	v_fmac_f32_e32 v139, v140, v132
	v_fma_f32 v0, -v0, v139, v138
	v_div_fmas_f32 v0, v0, v132, v139
	v_div_fixup_f32 v137, v0, v137, 1.0
	v_div_scale_f32 v0, s[28:29], v136, v136, 1.0
	v_rcp_f32_e32 v132, v0
	s_nop 0
	v_fma_f32 v138, -v0, v132, 1.0
	v_fmac_f32_e32 v132, v138, v132
	v_div_scale_f32 v138, vcc, 1.0, v136, 1.0
	v_mul_f32_e32 v139, v138, v132
	v_fma_f32 v140, -v0, v139, v138
	v_fmac_f32_e32 v139, v140, v132
	v_fma_f32 v0, -v0, v139, v138
	v_div_fmas_f32 v0, v0, v132, v139
	v_div_fixup_f32 v136, v0, v136, 1.0
	v_lshlrev_b32_e32 v0, 16, v133
	v_mul_f32_e32 v0, 0xbfb8aa3b, v0
	v_exp_f32_e32 v132, v0
	v_and_b32_e32 v0, 0xffff0000, v133
	v_mul_f32_e32 v0, 0xbfb8aa3b, v0
	v_exp_f32_e32 v133, v0
	v_pk_mul_f32 v[136:137], v[12:13], v[136:137]
	v_pk_add_f32 v[132:133], v[132:133], 1.0 op_sel_hi:[1,0]
	s_nop 0
	v_div_scale_f32 v0, s[28:29], v133, v133, 1.0
	v_rcp_f32_e32 v138, v0
	s_nop 0
	v_fma_f32 v139, -v0, v138, 1.0
	v_fmac_f32_e32 v138, v139, v138
	v_div_scale_f32 v139, vcc, 1.0, v133, 1.0
	v_mul_f32_e32 v140, v139, v138
	v_fma_f32 v141, -v0, v140, v139
	v_fmac_f32_e32 v140, v141, v138
	v_fma_f32 v0, -v0, v140, v139
	v_div_fmas_f32 v0, v0, v138, v140
	v_div_fixup_f32 v133, v0, v133, 1.0
	v_div_scale_f32 v0, s[28:29], v132, v132, 1.0
	v_rcp_f32_e32 v138, v0
	s_nop 0
	v_fma_f32 v139, -v0, v138, 1.0
	v_fmac_f32_e32 v138, v139, v138
	v_div_scale_f32 v139, vcc, 1.0, v132, 1.0
	v_mul_f32_e32 v140, v139, v138
	v_fma_f32 v141, -v0, v140, v139
	v_fmac_f32_e32 v140, v141, v138
	v_fma_f32 v0, -v0, v140, v139
	v_div_fmas_f32 v0, v0, v138, v140
	v_div_fixup_f32 v132, v0, v132, 1.0
	v_lshlrev_b32_e32 v0, 16, v134
	v_mul_f32_e32 v0, 0xbfb8aa3b, v0
	v_pk_mul_f32 v[138:139], v[14:15], v[132:133]
	v_exp_f32_e32 v132, v0
	v_and_b32_e32 v0, 0xffff0000, v134
	v_mul_f32_e32 v0, 0xbfb8aa3b, v0
	v_exp_f32_e32 v133, v0
	s_nop 0
	v_pk_add_f32 v[132:133], v[132:133], 1.0 op_sel_hi:[1,0]
	s_nop 0
	v_div_scale_f32 v0, s[28:29], v133, v133, 1.0
	v_rcp_f32_e32 v134, v0
	s_nop 0
	v_fma_f32 v140, -v0, v134, 1.0
	v_fmac_f32_e32 v134, v140, v134
	v_div_scale_f32 v140, vcc, 1.0, v133, 1.0
	v_mul_f32_e32 v141, v140, v134
	v_fma_f32 v142, -v0, v141, v140
	v_fmac_f32_e32 v141, v142, v134
	v_fma_f32 v0, -v0, v141, v140
	v_div_fmas_f32 v0, v0, v134, v141
	v_div_fixup_f32 v133, v0, v133, 1.0
	v_div_scale_f32 v0, s[28:29], v132, v132, 1.0
	v_rcp_f32_e32 v134, v0
	s_nop 0
	v_fma_f32 v140, -v0, v134, 1.0
	v_fmac_f32_e32 v134, v140, v134
	v_div_scale_f32 v140, vcc, 1.0, v132, 1.0
	v_mul_f32_e32 v141, v140, v134
	v_fma_f32 v142, -v0, v141, v140
	v_fmac_f32_e32 v141, v142, v134
	v_fma_f32 v0, -v0, v141, v140
	v_div_fmas_f32 v0, v0, v134, v141
	v_div_fixup_f32 v132, v0, v132, 1.0
	v_lshlrev_b32_e32 v0, 16, v135
	v_mul_f32_e32 v0, 0xbfb8aa3b, v0
	v_pk_mul_f32 v[140:141], v[16:17], v[132:133]
	v_exp_f32_e32 v132, v0
	v_and_b32_e32 v0, 0xffff0000, v135
	v_mul_f32_e32 v0, 0xbfb8aa3b, v0
	v_exp_f32_e32 v133, v0
	s_nop 0
	v_pk_add_f32 v[132:133], v[132:133], 1.0 op_sel_hi:[1,0]
	s_nop 0
	v_div_scale_f32 v0, s[28:29], v133, v133, 1.0
	v_rcp_f32_e32 v134, v0
	s_nop 0
	v_fma_f32 v135, -v0, v134, 1.0
	v_fmac_f32_e32 v134, v135, v134
	v_div_scale_f32 v135, vcc, 1.0, v133, 1.0
	v_mul_f32_e32 v142, v135, v134
	v_fma_f32 v143, -v0, v142, v135
	v_fmac_f32_e32 v142, v143, v134
	v_fma_f32 v0, -v0, v142, v135
	v_div_fmas_f32 v0, v0, v134, v142
	v_div_fixup_f32 v133, v0, v133, 1.0
	v_div_scale_f32 v0, s[28:29], v132, v132, 1.0
	v_rcp_f32_e32 v134, v0
	s_nop 0
	v_fma_f32 v135, -v0, v134, 1.0
	v_fmac_f32_e32 v134, v135, v134
	v_div_scale_f32 v135, vcc, 1.0, v132, 1.0
	v_mul_f32_e32 v142, v135, v134
	v_fma_f32 v143, -v0, v142, v135
	v_fmac_f32_e32 v142, v143, v134
	v_fma_f32 v0, -v0, v142, v135
	v_div_fmas_f32 v0, v0, v134, v142
	v_div_fixup_f32 v132, v0, v132, 1.0
	v_pk_mul_f32 v[142:143], v[18:19], v[132:133]
	v_cvt_pk_bf16_f32 v132, v136, v137
	v_cvt_pk_bf16_f32 v133, v138, v139
	v_cvt_pk_bf16_f32 v134, v140, v141
	v_cvt_pk_bf16_f32 v135, v142, v143
	global_store_dwordx4 v[2:3], v[132:135], off offset:256 sc1
	s_cbranch_execz .LBB0_74
